# tile-major layout for BOTH FFN-out operands: ACT (SwiGLU epilogue) and transposed w_o weights (P0) stored [panel][k-tile][row][128B]; FFN-out address constants changed to match
# speedup vs baseline: 1.0075x; 1.0009x over previous
; __device__ __forceinline__ unsigned cvt_pk_bf16(float lo, float hi) { const pk_f2_t v = {lo, hi}; return __builtin_bit_cast(unsigned, __builtin_convertvector(v, pk_bf2_t)); }
; #define GAS __attribute__((address_space(1)))
; #define LAS __attribute__((address_space(3)))
; #define LDS_WAIT() asm volatile("s_waitcnt lgkmcnt(0)" ::: "memory")
;     if (ldk == 0) ldk = K;
;     const int nblk = (N + 63) / 64, kb = item / nblk, nb = item % nblk, k0 = 64 * kb, n0 = 64 * nb;
;     const bool ok = n0 + lane < N;
;     float tv[64];
;     { const GAS float* wp = (const GAS float*)(W + (size_t)k0 * N + n0 + (ok ? lane : 0));
; #pragma unroll
;       for (int i = 0; i < 64; ++i) tv[i] = wp[(size_t)i * N]; }
; #pragma unroll
;     for (int j = 0; j < 32; ++j) scr[j * 65 + lane] = pg8::cvt_pk_bf16(tv[2 * j], tv[2 * j + 1]);
;     LDS_WAIT(); asm volatile("" ::: "memory");
;     const int c = lane & 7;
; #pragma unroll
;     for (int jj = 0; jj < 8; ++jj) { const int n = (lane >> 3) + 8 * jj; const LAS unsigned* q = scr + (4 * c) * 65 + n;
;         v4u o; o.x = q[0]; o.y = q[65]; o.z = q[130]; o.w = q[195];
;         if (n0 + n < N) *(GAS v4u*)(WT + (size_t)mp(n0 + n) * ldk + koff + k0 + 8 * c) = o; }
; __device__ __forceinline__ void p0_prologue(Frame& F, const Args& a) {
;     ...
;         if (r < 2 * I_FO) { const int f = r / I_FO; p0_transpose_item64(a.in[6] + ((size_t)l * 2 + f) * FF * D, FF, D, (bf16*)(ws + WS_WFO + ((size_t)l * 2 + f) * SZ_WFO1), MapIdent(), scu, r % I_FO, F.lane); continue; } r -= 2 * I_FO;
.LBB0_108:
	s_andn2_b64 vcc, exec, s[4:5]
	s_cbranch_vccnz .LBB0_110
	s_add_i32 s1, s31, 0xffffd400
	s_cmpk_gt_u32 s1, 0xaff
	s_cselect_b64 s[4:5], -1, 0
	v_cndmask_b32_e64 v2, 0, 1, s[4:5]
	s_lshl_b32 s26, s0, 1
	v_readfirstlane_b32 s4, v2
	s_or_b32 s4, s26, s4
	s_mul_i32 s26, s4, 0x2c00000
	s_mul_hi_i32 s5, s4, 0x2c00000
	s_add_u32 s27, s18, s26
	s_addc_u32 s28, s19, s5
	s_mul_hi_i32 s5, s4, 0x1600000
	s_mul_i32 s4, s4, 0x1600000
	s_add_u32 s4, s43, s4
	s_addc_u32 s5, s44, s5
	s_add_i32 s26, s31, 0xffffc900
	s_cmpk_lt_u32 s1, 0xb00
	s_cselect_b32 s1, s1, s26
	s_lshl_b32 s26, s1, 1
	s_and_b32 s26, s26, 0x1fc0
	s_lshl_b32 s1, s1, 6
	s_and_b32 s1, s1, 0x7c0
	s_lshl_b32 s29, s26, 13
	s_add_u32 s27, s27, s29
	s_addc_u32 s29, s28, 0
	s_lshl_b32 s28, s1, 2
	s_add_u32 s28, s27, s28
	s_addc_u32 s29, s29, 0
	v_mov_b32_e32 v15, v13
	v_lshl_add_u64 v[2:3], s[28:29], 0, v[14:15]
	s_movk_i32 s27, 0x2000
	v_add_co_u32_e32 v6, vcc, s27, v2
	s_movk_i32 s27, 0x4000
	s_nop 0
	v_addc_co_u32_e32 v7, vcc, 0, v3, vcc
	global_load_dword v5, v[6:7], off
	v_add_co_u32_e32 v6, vcc, s27, v2
	s_movk_i32 s27, 0x6000
	s_nop 0
	v_addc_co_u32_e32 v7, vcc, 0, v3, vcc
	v_add_co_u32_e32 v8, vcc, s27, v2
	global_load_dword v6, v[6:7], off
	s_nop 0
	v_addc_co_u32_e32 v9, vcc, 0, v3, vcc
	global_load_dword v7, v[8:9], off
	v_add_co_u32_e32 v8, vcc, s50, v2
	s_mov_b32 s27, 0xa000
	s_nop 0
	v_addc_co_u32_e32 v9, vcc, 0, v3, vcc
	v_add_co_u32_e32 v16, vcc, s27, v2
	s_mov_b32 s27, 0xc000
	s_nop 0
	v_addc_co_u32_e32 v17, vcc, 0, v3, vcc
	global_load_dword v8, v[8:9], off
	s_lshl_b32 s26, s26, 9
	s_lshr_b32 s100, s1, 8
	s_mul_i32 s100, s100, 0x2c0000
	s_add_u32 s26, s26, s100
	global_load_dword v9, v[16:17], off
	v_add_co_u32_e32 v16, vcc, s27, v2
	s_mov_b32 s27, 0xe000
	s_nop 0
	v_addc_co_u32_e32 v17, vcc, 0, v3, vcc
	global_load_dword v15, v[16:17], off
	v_add_co_u32_e32 v16, vcc, s27, v2
	s_mov_b32 s27, 0x12000
	s_nop 0
	v_addc_co_u32_e32 v17, vcc, 0, v3, vcc
	v_add_co_u32_e32 v38, vcc, s54, v2
	global_load_dword v16, v[16:17], off
	s_nop 0
	v_addc_co_u32_e32 v39, vcc, 0, v3, vcc
	global_load_dword v17, v[38:39], off
	v_add_co_u32_e32 v38, vcc, s27, v2
	s_mov_b32 s27, 0x14000
	s_nop 0
	v_addc_co_u32_e32 v39, vcc, 0, v3, vcc
	v_add_co_u32_e32 v40, vcc, s27, v2
	global_load_dword v38, v[38:39], off
	s_nop 0
	v_addc_co_u32_e32 v41, vcc, 0, v3, vcc
	global_load_dword v39, v[40:41], off
	v_add_co_u32_e32 v40, vcc, s57, v2
	s_mov_b32 s27, 0x18000
	s_nop 0
	v_addc_co_u32_e32 v41, vcc, 0, v3, vcc
	v_add_co_u32_e32 v42, vcc, s27, v2
	s_mov_b32 s27, 0x1a000
	s_nop 0
	v_addc_co_u32_e32 v43, vcc, 0, v3, vcc
	global_load_dword v40, v[40:41], off
	s_add_u32 s4, s4, s26
	global_load_dword v41, v[42:43], off
	v_add_co_u32_e32 v42, vcc, s27, v2
	s_mov_b32 s27, 0x1c000
	s_nop 0
	v_addc_co_u32_e32 v43, vcc, 0, v3, vcc
	v_add_co_u32_e32 v44, vcc, s27, v2
	s_mov_b32 s27, 0x1e000
	s_nop 0
	v_addc_co_u32_e32 v45, vcc, 0, v3, vcc
	global_load_dword v42, v[42:43], off
	s_addc_u32 s5, s5, 0
	global_load_dword v43, v[44:45], off
	v_add_co_u32_e32 v44, vcc, s27, v2
	global_load_dword v4, v14, s[28:29]
	s_nop 0
	v_addc_co_u32_e32 v45, vcc, 0, v3, vcc
	v_add_co_u32_e32 v46, vcc, s62, v2
	global_load_dword v44, v[44:45], off
	s_nop 0
	v_addc_co_u32_e32 v47, vcc, 0, v3, vcc
	global_load_dword v45, v[46:47], off
	v_add_co_u32_e32 v46, vcc, s63, v2
	s_nop 1
	v_addc_co_u32_e32 v47, vcc, 0, v3, vcc
	v_add_co_u32_e32 v48, vcc, s64, v2
	global_load_dword v46, v[46:47], off
	s_nop 0
	v_addc_co_u32_e32 v49, vcc, 0, v3, vcc
	global_load_dword v47, v[48:49], off
	v_add_co_u32_e32 v48, vcc, s65, v2
	s_nop 1
	v_addc_co_u32_e32 v49, vcc, 0, v3, vcc
	global_load_dword v50, v[48:49], off
	v_add_co_u32_e32 v48, vcc, s66, v2
	s_nop 1
	v_addc_co_u32_e32 v49, vcc, 0, v3, vcc
	global_load_dword v51, v[48:49], off
	v_add_co_u32_e32 v48, vcc, s67, v2
	s_nop 1
	v_addc_co_u32_e32 v49, vcc, 0, v3, vcc
	global_load_dword v52, v[48:49], off
	v_add_co_u32_e32 v48, vcc, s68, v2
	s_nop 1
	v_addc_co_u32_e32 v49, vcc, 0, v3, vcc
	global_load_dword v53, v[48:49], off
	v_add_co_u32_e32 v48, vcc, s69, v2
	s_nop 1
	v_addc_co_u32_e32 v49, vcc, 0, v3, vcc
	global_load_dword v54, v[48:49], off
	v_add_co_u32_e32 v48, vcc, s70, v2
	s_nop 1
	v_addc_co_u32_e32 v49, vcc, 0, v3, vcc
	global_load_dword v55, v[48:49], off
	v_add_co_u32_e32 v48, vcc, s71, v2
	s_nop 1
	v_addc_co_u32_e32 v49, vcc, 0, v3, vcc
	global_load_dword v56, v[48:49], off
	v_add_co_u32_e32 v48, vcc, s72, v2
	s_nop 1
	v_addc_co_u32_e32 v49, vcc, 0, v3, vcc
	global_load_dword v57, v[48:49], off
	v_add_co_u32_e32 v48, vcc, s73, v2
	s_nop 1
	v_addc_co_u32_e32 v49, vcc, 0, v3, vcc
	global_load_dword v58, v[48:49], off
	v_add_co_u32_e32 v48, vcc, s74, v2
	s_nop 1
	v_addc_co_u32_e32 v49, vcc, 0, v3, vcc
	global_load_dword v59, v[48:49], off
	v_add_co_u32_e32 v48, vcc, s75, v2
	s_nop 1
	v_addc_co_u32_e32 v49, vcc, 0, v3, vcc
	global_load_dword v60, v[48:49], off
	v_add_co_u32_e32 v48, vcc, s76, v2
	s_nop 1
	v_addc_co_u32_e32 v49, vcc, 0, v3, vcc
	global_load_dword v61, v[48:49], off
	v_add_co_u32_e32 v48, vcc, s77, v2
	s_nop 1
	v_addc_co_u32_e32 v49, vcc, 0, v3, vcc
	global_load_dword v62, v[48:49], off
	v_add_co_u32_e32 v48, vcc, s78, v2
	s_nop 1
	v_addc_co_u32_e32 v49, vcc, 0, v3, vcc
	global_load_dword v63, v[48:49], off
	v_add_co_u32_e32 v48, vcc, s79, v2
	s_nop 1
	v_addc_co_u32_e32 v49, vcc, 0, v3, vcc
	global_load_dword v64, v[48:49], off
	v_add_co_u32_e32 v48, vcc, s81, v2
	s_nop 1
	v_addc_co_u32_e32 v49, vcc, 0, v3, vcc
	global_load_dword v65, v[48:49], off
	v_add_co_u32_e32 v48, vcc, s61, v2
	s_nop 1
	v_addc_co_u32_e32 v49, vcc, 0, v3, vcc
	global_load_dword v66, v[48:49], off
; __device__ __forceinline__ unsigned cvt_pk_bf16(float lo, float hi) { const pk_f2_t v = {lo, hi}; return __builtin_bit_cast(unsigned, __builtin_convertvector(v, pk_bf2_t)); }
;     ...
;       for (int i = 0; i < 64; ++i) tv[i] = wp[(size_t)i * N]; }
; #pragma unroll
;     for (int j = 0; j < 32; ++j) scr[j * 65 + lane] = pg8::cvt_pk_bf16(tv[2 * j], tv[2 * j + 1]);
	v_add_co_u32_e32 v48, vcc, s82, v2
	s_nop 1
	v_addc_co_u32_e32 v49, vcc, 0, v3, vcc
	global_load_dword v67, v[48:49], off
	v_add_co_u32_e32 v48, vcc, s83, v2
	s_nop 1
	v_addc_co_u32_e32 v49, vcc, 0, v3, vcc
	global_load_dword v68, v[48:49], off
	v_add_co_u32_e32 v48, vcc, s84, v2
	s_nop 1
	v_addc_co_u32_e32 v49, vcc, 0, v3, vcc
	global_load_dword v69, v[48:49], off
	v_add_co_u32_e32 v48, vcc, s85, v2
	s_nop 1
	v_addc_co_u32_e32 v49, vcc, 0, v3, vcc
	global_load_dword v70, v[48:49], off
	v_add_co_u32_e32 v48, vcc, s86, v2
	s_nop 1
	v_addc_co_u32_e32 v49, vcc, 0, v3, vcc
	global_load_dword v71, v[48:49], off
	v_add_co_u32_e32 v48, vcc, s87, v2
	s_nop 1
	v_addc_co_u32_e32 v49, vcc, 0, v3, vcc
	global_load_dword v72, v[48:49], off
	v_add_co_u32_e32 v48, vcc, s88, v2
	s_nop 1
	v_addc_co_u32_e32 v49, vcc, 0, v3, vcc
	global_load_dword v73, v[48:49], off
	v_add_co_u32_e32 v48, vcc, s89, v2
	s_nop 1
	v_addc_co_u32_e32 v49, vcc, 0, v3, vcc
	global_load_dword v74, v[48:49], off
	v_add_co_u32_e32 v48, vcc, s90, v2
	s_nop 1
	v_addc_co_u32_e32 v49, vcc, 0, v3, vcc
	global_load_dword v75, v[48:49], off
	v_add_co_u32_e32 v48, vcc, s91, v2
	s_nop 1
	v_addc_co_u32_e32 v49, vcc, 0, v3, vcc
	global_load_dword v76, v[48:49], off
	v_add_co_u32_e32 v48, vcc, s92, v2
	s_nop 1
	v_addc_co_u32_e32 v49, vcc, 0, v3, vcc
	global_load_dword v77, v[48:49], off
	v_add_co_u32_e32 v48, vcc, s93, v2
	s_nop 1
	v_addc_co_u32_e32 v49, vcc, 0, v3, vcc
	global_load_dword v78, v[48:49], off
	v_add_co_u32_e32 v48, vcc, s94, v2
	s_nop 1
	v_addc_co_u32_e32 v49, vcc, 0, v3, vcc
	global_load_dword v79, v[48:49], off
	v_add_co_u32_e32 v48, vcc, s95, v2
	s_nop 1
	v_addc_co_u32_e32 v49, vcc, 0, v3, vcc
	global_load_dword v80, v[48:49], off
	v_add_co_u32_e32 v48, vcc, s96, v2
	s_nop 1
	v_addc_co_u32_e32 v49, vcc, 0, v3, vcc
	global_load_dword v81, v[48:49], off
	v_add_co_u32_e32 v48, vcc, s97, v2
	s_nop 1
	v_addc_co_u32_e32 v49, vcc, 0, v3, vcc
	global_load_dword v83, v[48:49], off
	v_add_co_u32_e32 v48, vcc, s24, v2
	s_nop 1
	v_addc_co_u32_e32 v49, vcc, 0, v3, vcc
	global_load_dword v84, v[48:49], off
	v_add_co_u32_e32 v48, vcc, s25, v2
	s_nop 1
	v_addc_co_u32_e32 v49, vcc, 0, v3, vcc
	global_load_dword v85, v[48:49], off
	v_add_co_u32_e32 v48, vcc, s37, v2
	s_nop 1
	v_addc_co_u32_e32 v49, vcc, 0, v3, vcc
	global_load_dword v86, v[48:49], off
	v_add_co_u32_e32 v48, vcc, s38, v2
	s_nop 1
	v_addc_co_u32_e32 v49, vcc, 0, v3, vcc
	global_load_dword v87, v[48:49], off
	v_add_co_u32_e32 v48, vcc, s39, v2
	s_nop 1
	v_addc_co_u32_e32 v49, vcc, 0, v3, vcc
	global_load_dword v88, v[48:49], off
	v_add_co_u32_e32 v48, vcc, s40, v2
	s_nop 1
	v_addc_co_u32_e32 v49, vcc, 0, v3, vcc
	global_load_dword v89, v[48:49], off
	v_add_co_u32_e32 v48, vcc, s22, v2
	s_nop 1
	v_addc_co_u32_e32 v49, vcc, 0, v3, vcc
	global_load_dword v90, v[48:49], off
	v_add_co_u32_e32 v48, vcc, s23, v2
	s_nop 1
	v_addc_co_u32_e32 v49, vcc, 0, v3, vcc
	global_load_dword v91, v[48:49], off
	v_add_co_u32_e32 v48, vcc, s41, v2
	s_nop 1
	v_addc_co_u32_e32 v49, vcc, 0, v3, vcc
	global_load_dword v92, v[48:49], off
	v_add_co_u32_e32 v48, vcc, s42, v2
	s_nop 1
	v_addc_co_u32_e32 v49, vcc, 0, v3, vcc
	global_load_dword v93, v[48:49], off
	v_add_co_u32_e32 v48, vcc, s33, v2
	s_nop 1
	v_addc_co_u32_e32 v49, vcc, 0, v3, vcc
	v_add_co_u32_e32 v2, vcc, s47, v2
	global_load_dword v48, v[48:49], off
	s_nop 0
	v_addc_co_u32_e32 v3, vcc, 0, v3, vcc
	global_load_dword v2, v[2:3], off
	s_waitcnt vmcnt(49)
	v_cvt_pk_bf16_f32 v3, v4, v5
	v_cvt_pk_bf16_f32 v4, v6, v7
	ds_write2_b32 v22, v3, v4 offset1:65
	v_cvt_pk_bf16_f32 v3, v8, v9
	v_cvt_pk_bf16_f32 v4, v15, v16
	ds_write2_b32 v22, v3, v4 offset0:130 offset1:195
	v_cvt_pk_bf16_f32 v3, v17, v38
	v_cvt_pk_bf16_f32 v4, v39, v40
	ds_write2_b32 v28, v3, v4 offset0:4 offset1:69
	v_cvt_pk_bf16_f32 v3, v41, v42
	s_waitcnt vmcnt(48)
	v_cvt_pk_bf16_f32 v4, v43, v44
	ds_write2_b32 v28, v3, v4 offset0:134 offset1:199
	s_waitcnt vmcnt(46)
	v_cvt_pk_bf16_f32 v3, v45, v46
	s_waitcnt vmcnt(44)
	v_cvt_pk_bf16_f32 v4, v47, v50
	ds_write2_b32 v29, v3, v4 offset0:8 offset1:73
	s_waitcnt vmcnt(42)
	v_cvt_pk_bf16_f32 v3, v51, v52
	s_waitcnt vmcnt(40)
	v_cvt_pk_bf16_f32 v4, v53, v54
	ds_write2_b32 v29, v3, v4 offset0:138 offset1:203
	s_waitcnt vmcnt(38)
	v_cvt_pk_bf16_f32 v3, v55, v56
	s_waitcnt vmcnt(36)
	v_cvt_pk_bf16_f32 v4, v57, v58
	ds_write2_b32 v30, v3, v4 offset0:12 offset1:77
	s_waitcnt vmcnt(34)
	v_cvt_pk_bf16_f32 v3, v59, v60
	s_waitcnt vmcnt(32)
	v_cvt_pk_bf16_f32 v4, v61, v62
	ds_write2_b32 v30, v3, v4 offset0:142 offset1:207
	s_waitcnt vmcnt(30)
; __device__ __forceinline__ unsigned cvt_pk_bf16(float lo, float hi) { const pk_f2_t v = {lo, hi}; return __builtin_bit_cast(unsigned, __builtin_convertvector(v, pk_bf2_t)); }
; #define GAS __attribute__((address_space(1)))
; #define LAS __attribute__((address_space(3)))
; #define LDS_WAIT() asm volatile("s_waitcnt lgkmcnt(0)" ::: "memory")
;     ...
;     for (int j = 0; j < 32; ++j) scr[j * 65 + lane] = pg8::cvt_pk_bf16(tv[2 * j], tv[2 * j + 1]);
;     LDS_WAIT(); asm volatile("" ::: "memory");
;     const int c = lane & 7;
; #pragma unroll
;     for (int jj = 0; jj < 8; ++jj) { const int n = (lane >> 3) + 8 * jj; const LAS unsigned* q = scr + (4 * c) * 65 + n;
;         v4u o; o.x = q[0]; o.y = q[65]; o.z = q[130]; o.w = q[195];
;         if (n0 + n < N) *(GAS v4u*)(WT + (size_t)mp(n0 + n) * ldk + koff + k0 + 8 * c) = o; }
	v_cvt_pk_bf16_f32 v3, v63, v64
	s_waitcnt vmcnt(28)
	v_cvt_pk_bf16_f32 v4, v65, v66
	ds_write2_b32 v31, v3, v4 offset0:16 offset1:81
	s_waitcnt vmcnt(26)
	v_cvt_pk_bf16_f32 v3, v67, v68
	s_waitcnt vmcnt(24)
	v_cvt_pk_bf16_f32 v4, v69, v70
	ds_write2_b32 v31, v3, v4 offset0:146 offset1:211
	s_waitcnt vmcnt(22)
	v_cvt_pk_bf16_f32 v3, v71, v72
	s_waitcnt vmcnt(20)
	v_cvt_pk_bf16_f32 v4, v73, v74
	ds_write2_b32 v32, v3, v4 offset0:20 offset1:85
	s_waitcnt vmcnt(18)
	v_cvt_pk_bf16_f32 v3, v75, v76
	s_waitcnt vmcnt(16)
	v_cvt_pk_bf16_f32 v4, v77, v78
	ds_write2_b32 v32, v3, v4 offset0:150 offset1:215
	s_waitcnt vmcnt(14)
	v_cvt_pk_bf16_f32 v3, v79, v80
	s_waitcnt vmcnt(12)
	v_cvt_pk_bf16_f32 v4, v81, v83
	ds_write2_b32 v33, v3, v4 offset0:24 offset1:89
	s_waitcnt vmcnt(10)
	v_cvt_pk_bf16_f32 v3, v84, v85
	s_waitcnt vmcnt(8)
	v_cvt_pk_bf16_f32 v4, v86, v87
	ds_write2_b32 v33, v3, v4 offset0:154 offset1:219
	v_or_b32_e32 v15, s1, v11
	v_lshl_add_u64 v[16:17], s[4:5], 0, v[12:13]
	s_waitcnt vmcnt(6)
	v_cvt_pk_bf16_f32 v3, v88, v89
	v_and_b32_e32 v42, 0xff, v15
	v_lshlrev_b32_e32 v42, 7, v42
	v_mov_b32_e32 v43, v13
	v_lshl_add_u64 v[42:43], v[16:17], 0, v[42:43]
	v_or_b32_e32 v15, s1, v19
	s_waitcnt vmcnt(4)
	v_cvt_pk_bf16_f32 v4, v90, v91
	ds_write2_b32 v34, v3, v4 offset0:28 offset1:93
	s_waitcnt vmcnt(2)
	v_cvt_pk_bf16_f32 v3, v92, v93
	s_waitcnt vmcnt(0)
	v_cvt_pk_bf16_f32 v2, v48, v2
	ds_write2_b32 v34, v3, v2 offset0:158 offset1:223
	s_waitcnt lgkmcnt(0)
	ds_read2_b32 v[2:3], v23 offset0:65 offset1:73
	ds_read2_b32 v[38:39], v23 offset0:130 offset1:138
	ds_read2_b32 v[4:5], v23 offset0:195 offset1:203
	ds_read2_b32 v[40:41], v23 offset1:8
	s_waitcnt lgkmcnt(3)
	v_mov_b32_e32 v7, v2
	s_waitcnt lgkmcnt(2)
	v_mov_b32_e32 v8, v38
	s_waitcnt lgkmcnt(1)
	v_mov_b32_e32 v9, v4
	s_waitcnt lgkmcnt(0)
	v_mov_b32_e32 v6, v40
	global_store_dwordx4 v[42:43], v[6:9], off
	v_mov_b32_e32 v2, v41
	v_mov_b32_e32 v4, v39
	v_or_b32_e32 v6, s1, v18
	v_and_b32_e32 v6, 0xff, v6
	v_lshlrev_b32_e32 v6, 7, v6
	v_mov_b32_e32 v7, v13
	v_lshl_add_u64 v[6:7], v[16:17], 0, v[6:7]
	global_store_dwordx4 v[6:7], v[2:5], off
	ds_read2_b32 v[38:39], v23 offset0:16 offset1:24
	ds_read2_b32 v[2:3], v23 offset0:81 offset1:89
	ds_read2_b32 v[40:41], v23 offset0:146 offset1:154
	ds_read2_b32 v[4:5], v23 offset0:211 offset1:219
	v_and_b32_e32 v42, 0xff, v15
	v_lshlrev_b32_e32 v42, 7, v42
	v_mov_b32_e32 v43, v13
	s_waitcnt lgkmcnt(3)
	v_mov_b32_e32 v6, v38
	s_waitcnt lgkmcnt(2)
	v_mov_b32_e32 v7, v2
	s_waitcnt lgkmcnt(1)
	v_mov_b32_e32 v8, v40
	s_waitcnt lgkmcnt(0)
	v_mov_b32_e32 v9, v4
	v_lshl_add_u64 v[42:43], v[16:17], 0, v[42:43]
	global_store_dwordx4 v[42:43], v[6:9], off
	v_mov_b32_e32 v2, v39
	v_mov_b32_e32 v4, v41
	v_or_b32_e32 v6, s1, v20
	v_and_b32_e32 v6, 0xff, v6
	v_lshlrev_b32_e32 v6, 7, v6
	v_mov_b32_e32 v7, v13
	v_lshl_add_u64 v[6:7], v[16:17], 0, v[6:7]
	global_store_dwordx4 v[6:7], v[2:5], off
	ds_read2_b32 v[38:39], v23 offset0:32 offset1:40
	ds_read2_b32 v[2:3], v23 offset0:97 offset1:105
	ds_read2_b32 v[40:41], v23 offset0:162 offset1:170
	ds_read2_b32 v[4:5], v23 offset0:227 offset1:235
	v_or_b32_e32 v15, s1, v24
	v_and_b32_e32 v42, 0xff, v15
	v_lshlrev_b32_e32 v42, 7, v42
	v_mov_b32_e32 v43, v13
	s_waitcnt lgkmcnt(3)
	v_mov_b32_e32 v6, v38
	s_waitcnt lgkmcnt(2)
	v_mov_b32_e32 v7, v2
	s_waitcnt lgkmcnt(1)
	v_mov_b32_e32 v8, v40
	s_waitcnt lgkmcnt(0)
	v_mov_b32_e32 v9, v4
	v_lshl_add_u64 v[42:43], v[16:17], 0, v[42:43]
	global_store_dwordx4 v[42:43], v[6:9], off
	v_mov_b32_e32 v2, v39
	v_mov_b32_e32 v4, v41
	v_or_b32_e32 v6, s1, v25
	v_and_b32_e32 v6, 0xff, v6
	v_lshlrev_b32_e32 v6, 7, v6
	v_mov_b32_e32 v7, v13
	v_lshl_add_u64 v[6:7], v[16:17], 0, v[6:7]
	global_store_dwordx4 v[6:7], v[2:5], off
	ds_read2_b32 v[38:39], v23 offset0:48 offset1:56
	ds_read2_b32 v[2:3], v23 offset0:113 offset1:121
	ds_read2_b32 v[40:41], v23 offset0:178 offset1:186
	ds_read2_b32 v[4:5], v23 offset0:243 offset1:251
	v_or_b32_e32 v15, s1, v26
	v_and_b32_e32 v42, 0xff, v15
	v_lshlrev_b32_e32 v42, 7, v42
	v_mov_b32_e32 v43, v13
	s_waitcnt lgkmcnt(3)
	v_mov_b32_e32 v6, v38
	s_waitcnt lgkmcnt(2)
	v_mov_b32_e32 v7, v2
	s_waitcnt lgkmcnt(1)
	v_mov_b32_e32 v8, v40
	s_waitcnt lgkmcnt(0)
	v_mov_b32_e32 v9, v4
	v_lshl_add_u64 v[42:43], v[16:17], 0, v[42:43]
	global_store_dwordx4 v[42:43], v[6:9], off
	v_mov_b32_e32 v2, v39
	v_mov_b32_e32 v4, v41
	v_or_b32_e32 v6, s1, v27
	v_and_b32_e32 v6, 0xff, v6
	v_lshlrev_b32_e32 v6, 7, v6
	v_mov_b32_e32 v7, v13
	v_lshl_add_u64 v[6:7], v[16:17], 0, v[6:7]
	global_store_dwordx4 v[6:7], v[2:5], off
	s_waitcnt lgkmcnt(0)

; #define PG8_STAGE(bufoff, gbase, voff) do { _Pragma("unroll") for (int _i = 0; _i < 2; ++_i) \
;         __builtin_amdgcn_global_load_lds((const unsigned*)((const char*)(gbase) + (voff)[_i]), (PG8_LAS unsigned*)(lds + (bufoff) + ldsw + _i * 8192), 16, 0, 0); } while (0)
; #define PG8_BAR __builtin_amdgcn_s_barrier()
; template <class Epi, class Sched, bool ALIGN_EPI = false, bool SP2 = false>
; __device__ __forceinline__ void gemm_phase(PG8_LAS unsigned char* lds, const Gemm g, const Sched& S, const Epi& E, int wave_s) {
;     ...
;     const int tid = tid_, wid = __builtin_amdgcn_readfirstlane(tid >> 6), lane = tid & 63, wr = wid >> 2, wc = wid & 3, fr = lane & 15, fq = lane >> 4;
;     const int K = g.K, nt = K / BK;
;     unsigned voffA[2], voffB[2];
; #pragma unroll
;     for (int i = 0; i < 2; ++i) { int R, C; stage_rc(tid * 16 + i * 8192, R, C); const int Rb = Epi::PERM ? ((R & ~31) + perm32(R & 31)) : R;
;         voffA[i] = (unsigned)(R * g.lda + C) * 2u; voffB[i] = (unsigned)(Rb * g.ldb + C) * 2u; }
;     const size_t kstep = (size_t)(BK * 2);
;     const size_t hstepA = (size_t)HALF * g.lda * 2, hstepB = (size_t)HALF * g.ldb * 2;
;     const size_t tstepA = 2 * hstepA, tstepB = 2 * hstepB;
;     const unsigned ldsw = (unsigned)wid * 1024u;
;     const int aoff = lds_byte(wr * 64 + fr, fq * 8), boff = lds_byte(wc * 32 + fr, fq * 8);
;     ...
;     Unit cur, nxt; int ui = 0;
;     if (!S.next(0, cur)) return;
;     f32x4 acc[2][2][4][2];
; #pragma unroll
;     for (int a = 0; a < 2; ++a)
; #pragma unroll
;         for (int b = 0; b < 2; ++b)
; #pragma unroll
;             for (int m = 0; m < 4; ++m)
; #pragma unroll
;                 for (int n = 0; n < 2; ++n) acc[a][b][m][n] = (f32x4){0.f, 0.f, 0.f, 0.f};
;     bf16x8 At[4][2], B0[2][2], B1[2][2];
;     const char* cA = (const char*)g.A + (size_t)cur.pm * tstepA; const char* cB = (const char*)g.Bt + (size_t)cur.pn * tstepB;
;     S.a_ready(cur);
;     if constexpr (SP2) {
;         PG8_STAGE(PG8_SB(0, 0), cB, voffB); PG8_STAGE(PG8_SB(0, 1), cB + hstepB, voffB); PG8_STAGE(PG8_SA(0, 0), cA, voffA); PG8_STAGE(PG8_SA(0, 1), cA + hstepA, voffA);
;         if (wr == 1) PG8_BAR;
;         PG8_WAIT_V(2); PG8_BAR;
;         PG8_STAGE(PG8_SB(1, 0), cB + kstep, voffB); PG8_STAGE(PG8_SA(1, 0), cA + kstep, voffA); PG8_STAGE(PG8_SB(1, 1), cB + hstepB + kstep, voffB);
;         PG8_WAIT_V(6); PG8_BAR;
.LBB0_341:
	v_mov_b32_e32 v0, v1
	s_andn2_b32 s2, s2, 63
	v_mbcnt_lo_u32_b32 v0, -1, v0
	v_mbcnt_hi_u32_b32 v0, -1, v0
	v_readlane_b32 s6, v254, 2
	v_or_b32_e32 v18, s2, v0
	v_readlane_b32 s7, v254, 3
	s_andn2_b64 vcc, exec, s[6:7]
	v_readfirstlane_b32 s12, v18
	s_cbranch_vccnz .LBB0_365
	v_lshlrev_b32_e32 v0, 4, v18
	v_add_u32_e32 v2, 0x2000, v0
	v_ashrrev_i32_e32 v3, 31, v2
	v_lshrrev_b32_e32 v3, 22, v3
	v_add_u32_e32 v3, v2, v3
	v_ashrrev_i32_e32 v10, 10, v3
	v_mul_i32_i24_e32 v3, 0x400, v10
	v_sub_u32_e32 v2, v2, v3
	v_lshrrev_b32_e32 v3, 4, v2
	v_bitop3_b32 v2, v3, v2, 32 bitop3:0x6c
	v_ashrrev_i32_e32 v3, 31, v2
	v_lshrrev_b32_e32 v3, 26, v3
	v_add_u32_e32 v3, v2, v3
	v_ashrrev_i32_e32 v11, 6, v3
	v_lshlrev_b32_e32 v5, 5, v10
	v_and_b32_e32 v3, 0xc0, v3
	v_and_b32_e32 v12, 32, v5
	v_sub_u32_e32 v2, v2, v3
	v_mov_b32_e32 v5, 1
	v_ashrrev_i16_sdwa v2, v5, sext(v2) dst_sel:DWORD dst_unused:UNUSED_PAD src0_sel:DWORD src1_sel:BYTE_0
	v_bfe_i32 v13, v2, 0, 16
	v_bfe_i32 v2, v18, 27, 1
	v_lshrrev_b32_e32 v2, 22, v2
	v_add_u32_e32 v2, v0, v2
	v_and_b32_e32 v2, 0xfffffc00, v2
	v_sub_u32_e32 v0, v0, v2
	s_add_u32 s2, s10, 0x22d90000
	v_lshrrev_b32_e32 v2, 4, v0
	v_ashrrev_i32_e32 v3, 31, v18
	s_addc_u32 s22, s11, 0
	s_mul_i32 s6, s78, 0x2c00000
	v_bitop3_b32 v0, v2, v0, 32 bitop3:0x6c
	v_lshrrev_b32_e32 v3, 26, v3
	s_add_u32 s6, s10, s6
	v_lshlrev_b32_e32 v4, 3, v10
	v_ashrrev_i32_e32 v2, 31, v0
	v_add_u32_e32 v3, v18, v3
	s_addc_u32 s7, s11, 0
	v_and_b32_e32 v4, 0x7ffff0, v4
	v_lshrrev_b32_e32 v2, 26, v2
	v_ashrrev_i32_e32 v15, 6, v3
	s_add_u32 s33, s6, 0xb190000
	v_add_u32_e32 v4, v11, v4
	s_movk_i32 s6, 64
	v_add_u32_e32 v2, v0, v2
	v_lshlrev_b32_e32 v3, 3, v15
	v_lshl_or_b32 v228, v4, 6, v12
	v_add_lshl_u32 v228, v228, v13, 1
	v_mov_b32_e32 v229, 0
	v_mul_lo_u32 v4, v4, s6
	v_ashrrev_i32_e32 v14, 6, v2
	v_and_b32_e32 v3, 0x7ffff0, v3
	s_addc_u32 s36, s7, 0
	s_ashr_i32 s13, s12, 6
	v_or_b32_e32 v4, v4, v12
	v_add_u32_e32 v3, v14, v3
	v_and_b32_e32 v2, 0xc0, v2
	s_ashr_i32 s14, s12, 8
	s_lshl_b32 s37, s13, 10
	s_waitcnt vmcnt(0)
	v_add_lshl_u32 v130, v4, v13, 1
	v_mov_b32_e32 v226, v3
	v_mul_lo_u32 v3, v3, s6
	v_lshlrev_b32_e32 v4, 5, v15
	v_sub_u32_e32 v0, v0, v2
	v_readlane_b32 s6, v255, 22
	v_and_b32_e32 v16, 32, v4
	v_ashrrev_i16_sdwa v0, v5, sext(v0) dst_sel:DWORD dst_unused:UNUSED_PAD src0_sel:DWORD src1_sel:BYTE_0
	s_add_u32 s18, s33, s6
	v_readlane_b32 s6, v255, 20
	v_or_b32_e32 v3, v3, v16
	v_bfe_i32 v17, v0, 0, 16
	s_addc_u32 s19, s36, s6
	s_add_i32 s42, s37, 0
	v_add_lshl_u32 v0, v3, v17, 1
	v_lshl_or_b32 v226, v226, 6, v16
	v_add_lshl_u32 v226, v226, v17, 1
	v_mov_b32_e32 v227, 0
	s_add_i32 m0, s42, 0x10000
	v_mov_b32_e32 v131, v1
	global_load_lds_dwordx4 v0, s[18:19]
	s_add_i32 m0, s42, 0x12000
	s_add_u32 s6, s18, 0x4000
	global_load_lds_dwordx4 v130, s[18:19]
	s_addc_u32 s7, s19, 0
	s_add_i32 m0, s42, 0x14000
	v_lshl_add_u64 v[8:9], s[18:19], 0, v[0:1]
	global_load_lds_dwordx4 v0, s[6:7]
	s_add_i32 m0, s42, 0x16000
	v_lshl_add_u64 v[6:7], s[18:19], 0, v[130:131]
	global_load_lds_dwordx4 v130, s[6:7]
	v_readlane_b32 s6, v255, 19
	s_add_u32 s16, s2, s6
	v_readlane_b32 s6, v255, 16
	s_addc_u32 s17, s22, s6
	s_add_i32 s43, s42, 0x2000
	s_mov_b32 m0, s42
	s_add_u32 s6, s16, 0x4000
	global_load_lds_dwordx4 v226, s[16:17]
	s_mov_b32 m0, s43
	s_addc_u32 s7, s17, 0
	s_add_i32 s44, s42, 0x4000
	global_load_lds_dwordx4 v228, s[16:17]
	s_mov_b32 m0, s44
	s_add_i32 s45, s42, 0x6000
	global_load_lds_dwordx4 v226, s[6:7]
	s_mov_b32 m0, s45
	s_cmp_eq_u32 s14, 1
	global_load_lds_dwordx4 v228, s[6:7]
	v_lshl_add_u64 v[2:3], s[16:17], 0, v[226:227]
	s_cselect_b64 s[6:7], -1, 0
	s_cmp_lg_u32 s14, 1
	v_lshl_add_u64 v[4:5], s[16:17], 0, v[228:229]
	s_cbranch_scc1 .LBB0_344
	s_barrier
.LBB0_344:
	s_add_u32 s8, s10, 0x16d90000
	s_addc_u32 s9, s11, 0
	s_mul_i32 s15, s78, 0x48000
	s_add_u32 s10, s10, s15
	s_addc_u32 s11, s11, 0
	v_bfe_u32 v19, v18, 4, 2
	s_add_u32 s46, s10, 0x104000
	v_and_b32_e32 v20, 15, v18
	v_lshlrev_b32_e32 v21, 4, v19
	v_lshlrev_b32_e32 v18, 2, v18
	s_addc_u32 s47, s11, 0
	v_lshl_or_b32 v158, s14, 6, v20
	v_lshl_or_b32 v20, v20, 6, v21
	s_lshl_b32 s10, s14, 13
	v_and_b32_e32 v18, 32, v18
	v_bitop3_b32 v21, v20, s10, v18 bitop3:0xde
	s_lshl_b32 s10, s13, 5
	s_and_b32 s13, s10, 0x60
	s_add_i32 m0, s42, 0x18000
	s_mov_b64 s[100:101], 0x8000
	v_lshl_add_u64 v[8:9], v[8:9], 0, s[100:101]
	s_lshl_b32 s10, s13, 7
	s_waitcnt vmcnt(2)
	s_barrier
	global_load_lds_dwordx4 v[8:9], off
	v_lshl_add_u64 v[6:7], v[6:7], 0, s[100:101]
	s_add_i32 m0, s42, 0x1a000
	s_add_i32 s48, s42, 0x8000
	s_add_i32 s49, s42, 0xa000
	v_bitop3_b32 v159, v20, s10, v18 bitop3:0xde
	global_load_lds_dwordx4 v[6:7], off
	s_mov_b64 s[100:101], 0x8000
	v_lshl_add_u64 v[2:3], v[2:3], 0, s[100:101]
	s_mov_b32 m0, s48
	s_add_u32 s10, s18, 0xc000
	global_load_lds_dwordx4 v[2:3], off
	v_lshl_add_u64 v[2:3], v[4:5], 0, s[100:101]
	s_mov_b32 m0, s49
	s_addc_u32 s11, s19, 0
	global_load_lds_dwordx4 v[2:3], off
	s_add_i32 m0, s42, 0x1c000
	v_lshl_add_u64 v[2:3], s[10:11], 0, v[0:1]
	global_load_lds_dwordx4 v[2:3], off
	v_lshl_add_u64 v[2:3], s[10:11], 0, v[130:131]
	s_add_i32 m0, s42, 0x1e000
	s_movk_i32 s15, 0x1600
	global_load_lds_dwordx4 v[2:3], off
	v_lshrrev_b32_e32 v3, 1, v10
	v_mul_lo_u32 v2, v11, s15
	s_mov_b32 s14, 0x16000
	s_cmpk_lt_u32 s12, 0x100
	v_lshl_or_b32 v160, v19, 2, s13
	v_mad_u64_u32 v[2:3], s[12:13], v3, s14, v[2:3]
	v_or_b32_e32 v2, v2, v12
	v_add_lshl_u32 v2, v2, v13, 1
	v_mov_b32_e32 v3, v1
	s_mov_b64 s[20:21], 0x160080
	s_mov_b64 s[100:101], 0xc000
	v_lshl_add_u64 v[132:133], v[228:229], 0, s[100:101]
	v_lshrrev_b32_e32 v3, 1, v15
	v_mul_lo_u32 v2, v14, s15
	v_mad_u64_u32 v[2:3], s[12:13], v3, s14, v[2:3]
	s_waitcnt vmcnt(6)
	v_or_b32_e32 v2, v2, v16
	v_add_lshl_u32 v2, v2, v17, 1
	v_mov_b32_e32 v3, v1
	v_readlane_b32 s12, v255, 17
	s_cselect_b64 s[10:11], -1, 0
	v_lshl_add_u64 v[134:135], v[226:227], 0, s[100:101]
	s_mov_b32 s50, 0
	v_add_u32_e32 v161, 0, v21
	v_readlane_b32 s26, v255, 21
	s_mov_b32 s55, s12
	s_barrier
	v_readlane_b32 s13, v255, 18
	s_branch .LBB0_347

; #define PG8_STAGE(bufoff, gbase, voff) do { _Pragma("unroll") for (int _i = 0; _i < 2; ++_i) \
;         __builtin_amdgcn_global_load_lds((const unsigned*)((const char*)(gbase) + (voff)[_i]), (PG8_LAS unsigned*)(lds + (bufoff) + ldsw + _i * 8192), 16, 0, 0); } while (0)
; #define PG8_LDA(dst, b, h) do { _Pragma("unroll") for (int m = 0; m < 4; ++m) _Pragma("unroll") for (int k = 0; k < 2; ++k) dst[m][k] = *(const PG8_LAS bf16x8*)(lds + PG8_SA(b, h) + aoff + m * 2048 + k * 1024); } while (0)
; #define PG8_LDB(dst, b, h) do { _Pragma("unroll") for (int n = 0; n < 2; ++n) _Pragma("unroll") for (int k = 0; k < 2; ++k) dst[n][k] = *(const PG8_LAS bf16x8*)(lds + PG8_SB(b, h) + boff + n * 2048 + k * 1024); } while (0)
; #define PG8_WAIT_V(n) asm volatile("s_waitcnt vmcnt(" #n ")" ::: "memory")
; #define PG8_WAIT_L(n) asm volatile("s_waitcnt lgkmcnt(" #n ")" ::: "memory")
; #define PG8_BAR __builtin_amdgcn_s_barrier()
; #define PG8_SCHED __builtin_amdgcn_sched_barrier(0)
; template <class Epi, class Sched, bool ALIGN_EPI = false, bool SP2 = false>
; __device__ __forceinline__ void gemm_phase(PG8_LAS unsigned char* lds, const Gemm g, const Sched& S, const Epi& E, int wave_s) {
;     ...
;         for (int t = 0; t < nt; t += 2) {
;             const bool last = (t == nt - 2);
;             const char* a1 = cA + (size_t)(t + 1) * kstep;
;             const char* a2 = last ? nA : cA + (size_t)(t + 2) * kstep; const char* b2 = last ? nB : cB + (size_t)(t + 2) * kstep;
;             const char* a3 = a2 + kstep; const char* b3 = b2 + kstep;
;             if (last && has_next) S.a_ready(nxt);
;             if constexpr (Epi::HAS_MID) { if (t == nt / 2) E.mid(acc, cur, wr, wc, fr, fq); }
;             if constexpr (SP2) {
;             PG8_LDB(B0, 0, 0); PG8_LDB(B1, 0, 1); PG8_SCHED; PG8_LDA(At, 0, 0); PG8_STAGE(PG8_SA(1, 1), a1 + hstepA, voffA);
;             PG8_WAIT_V(8); PG8_WAIT_L(0); PG8_BAR; PG8_MMA(0, 0, At, B0); PG8_MMA(0, 1, At, B1); PG8_BAR; PG8_SCHED;
;     ...
;         for (int a = 0; a < 2; ++a)
; #pragma unroll
;             for (int b = 0; b < 2; ++b)
; #pragma unroll
;                 for (int m = 0; m < 4; ++m)
; #pragma unroll
;                     for (int n = 0; n < 2; ++n) acc[a][b][m][n] = (f32x4){0.f, 0.f, 0.f, 0.f};
;         cur = nxt; cA = nA; cB = nB; ++ui;
.LBB0_357:
	s_add_u32 s27, s18, 0x10000
	v_mov_b32_e32 v2, 0
	s_addc_u32 s40, s19, 0
	s_mov_b32 s41, -2
	v_mov_b32_e32 v3, v2
	v_mov_b32_e32 v4, v2
	v_mov_b32_e32 v5, v2
	v_mov_b32_e32 v6, v2
	v_mov_b32_e32 v7, v2
	v_mov_b32_e32 v8, v2
	v_mov_b32_e32 v9, v2
	v_mov_b32_e32 v18, v2
	v_mov_b32_e32 v19, v2
	v_mov_b32_e32 v20, v2
	v_mov_b32_e32 v21, v2
	v_mov_b32_e32 v22, v2
	v_mov_b32_e32 v23, v2
	v_mov_b32_e32 v24, v2
	v_mov_b32_e32 v25, v2
	v_mov_b32_e32 v34, v2
	v_mov_b32_e32 v35, v2
	v_mov_b32_e32 v36, v2
	v_mov_b32_e32 v37, v2
	v_mov_b32_e32 v38, v2
	v_mov_b32_e32 v39, v2
	v_mov_b32_e32 v40, v2
	v_mov_b32_e32 v41, v2
	v_mov_b32_e32 v50, v2
	v_mov_b32_e32 v51, v2
	v_mov_b32_e32 v52, v2
	v_mov_b32_e32 v53, v2
	v_mov_b32_e32 v54, v2
	v_mov_b32_e32 v55, v2
	v_mov_b32_e32 v56, v2
	v_mov_b32_e32 v57, v2
	v_mov_b32_e32 v10, v2
	v_mov_b32_e32 v11, v2
	v_mov_b32_e32 v12, v2
	v_mov_b32_e32 v13, v2
	v_mov_b32_e32 v14, v2
	v_mov_b32_e32 v15, v2
	v_mov_b32_e32 v16, v2
	v_mov_b32_e32 v17, v2
	v_mov_b32_e32 v26, v2
	v_mov_b32_e32 v27, v2
	v_mov_b32_e32 v28, v2
	v_mov_b32_e32 v29, v2
	v_mov_b32_e32 v30, v2
	v_mov_b32_e32 v31, v2
	v_mov_b32_e32 v32, v2
	v_mov_b32_e32 v33, v2
	v_mov_b32_e32 v42, v2
	v_mov_b32_e32 v43, v2
	v_mov_b32_e32 v44, v2
	v_mov_b32_e32 v45, v2
	v_mov_b32_e32 v46, v2
	v_mov_b32_e32 v47, v2
	v_mov_b32_e32 v48, v2
	v_mov_b32_e32 v49, v2
	v_mov_b32_e32 v58, v2
	v_mov_b32_e32 v59, v2
	v_mov_b32_e32 v60, v2
	v_mov_b32_e32 v61, v2
	v_mov_b32_e32 v62, v2
	v_mov_b32_e32 v63, v2
	v_mov_b32_e32 v64, v2
	v_mov_b32_e32 v65, v2
	v_mov_b32_e32 v66, v2
	v_mov_b32_e32 v67, v2
	v_mov_b32_e32 v68, v2
	v_mov_b32_e32 v69, v2
	v_mov_b32_e32 v70, v2
	v_mov_b32_e32 v71, v2
	v_mov_b32_e32 v72, v2
	v_mov_b32_e32 v73, v2
	v_mov_b32_e32 v82, v2
	v_mov_b32_e32 v83, v2
	v_mov_b32_e32 v84, v2
	v_mov_b32_e32 v85, v2
	v_mov_b32_e32 v86, v2
	v_mov_b32_e32 v87, v2
	v_mov_b32_e32 v88, v2
	v_mov_b32_e32 v89, v2
	v_mov_b32_e32 v98, v2
	v_mov_b32_e32 v99, v2
	v_mov_b32_e32 v100, v2
	v_mov_b32_e32 v101, v2
	v_mov_b32_e32 v102, v2
	v_mov_b32_e32 v103, v2
	v_mov_b32_e32 v104, v2
	v_mov_b32_e32 v105, v2
	v_mov_b32_e32 v114, v2
	v_mov_b32_e32 v115, v2
	v_mov_b32_e32 v116, v2
	v_mov_b32_e32 v117, v2
	v_mov_b32_e32 v118, v2
	v_mov_b32_e32 v119, v2
	v_mov_b32_e32 v120, v2
	v_mov_b32_e32 v121, v2
	v_mov_b32_e32 v74, v2
	v_mov_b32_e32 v75, v2
	v_mov_b32_e32 v76, v2
	v_mov_b32_e32 v77, v2
	v_mov_b32_e32 v78, v2
	v_mov_b32_e32 v79, v2
	v_mov_b32_e32 v80, v2
	v_mov_b32_e32 v81, v2
	v_mov_b32_e32 v90, v2
	v_mov_b32_e32 v91, v2
	v_mov_b32_e32 v92, v2
	v_mov_b32_e32 v93, v2
	v_mov_b32_e32 v94, v2
	v_mov_b32_e32 v95, v2
	v_mov_b32_e32 v96, v2
	v_mov_b32_e32 v97, v2
	v_mov_b32_e32 v106, v2
	v_mov_b32_e32 v107, v2
	v_mov_b32_e32 v108, v2
	v_mov_b32_e32 v109, v2
	v_mov_b32_e32 v110, v2
	v_mov_b32_e32 v111, v2
	v_mov_b32_e32 v112, v2
	v_mov_b32_e32 v113, v2
	v_mov_b32_e32 v122, v2
	v_mov_b32_e32 v123, v2
	v_mov_b32_e32 v124, v2
	v_mov_b32_e32 v125, v2
	v_mov_b32_e32 v126, v2
	v_mov_b32_e32 v127, v2
	v_mov_b32_e32 v128, v2
	v_mov_b32_e32 v129, v2
.LBB0_358:
	s_add_u32 s18, s16, 0x10000
	s_addc_u32 s19, s17, 0
	s_add_i32 s34, 0, 0x10000
	s_cmpk_eq_i32 s41, 0x54
	s_cselect_b32 s25, s13, s19
	s_cselect_b32 s24, s12, s18
	s_cselect_b32 s21, s15, s40
	s_cselect_b32 s20, s14, s27
	s_add_i32 s35, 0, 0x14000
	v_add_u32_e32 v148, s34, v159
	v_add_u32_e32 v156, s35, v159
	ds_read_b128 v[136:139], v148
	ds_read_b128 v[140:143], v148 offset:1024
	ds_read_b128 v[144:147], v148 offset:2048
	ds_read_b128 v[148:151], v148 offset:3072
	ds_read_b128 v[152:155], v156
	ds_read_b128 v[162:165], v156 offset:1024
	ds_read_b128 v[166:169], v156 offset:2048
	ds_read_b128 v[176:179], v156 offset:3072
	v_lshl_add_u64 v[156:157], s[16:17], 0, v[134:135]
	s_add_i32 m0, s42, 0xc000
	ds_read_b128 v[180:183], v161
	ds_read_b128 v[184:187], v161 offset:1024
	ds_read_b128 v[188:191], v161 offset:2048
	ds_read_b128 v[192:195], v161 offset:3072
	ds_read_b128 v[196:199], v161 offset:4096
	ds_read_b128 v[208:211], v161 offset:5120
	ds_read_b128 v[212:215], v161 offset:6144
	ds_read_b128 v[216:219], v161 offset:7168
	global_load_lds_dwordx4 v[156:157], off
	v_lshl_add_u64 v[156:157], s[16:17], 0, v[132:133]
	s_add_i32 m0, s42, 0xe000
	s_nop 0
	global_load_lds_dwordx4 v[156:157], off
	s_waitcnt vmcnt(8)
	s_waitcnt lgkmcnt(0)
	s_barrier
	s_setprio 1
	s_waitcnt lgkmcnt(0)
	v_mfma_f32_16x16x32_bf16 v[126:129], v[180:183], v[136:139], v[126:129]
	v_mfma_f32_16x16x32_bf16 v[122:125], v[180:183], v[144:147], v[122:125]
	v_mfma_f32_16x16x32_bf16 v[110:113], v[188:191], v[136:139], v[110:113]
	v_mfma_f32_16x16x32_bf16 v[106:109], v[188:191], v[144:147], v[106:109]
	v_mfma_f32_16x16x32_bf16 v[94:97], v[196:199], v[136:139], v[94:97]
	v_mfma_f32_16x16x32_bf16 v[90:93], v[196:199], v[144:147], v[90:93]
	v_mfma_f32_16x16x32_bf16 v[78:81], v[212:215], v[136:139], v[78:81]
	v_mfma_f32_16x16x32_bf16 v[74:77], v[212:215], v[144:147], v[74:77]
	v_mfma_f32_16x16x32_bf16 v[126:129], v[184:187], v[140:143], v[126:129]
	v_mfma_f32_16x16x32_bf16 v[122:125], v[184:187], v[148:151], v[122:125]
	v_mfma_f32_16x16x32_bf16 v[110:113], v[192:195], v[140:143], v[110:113]
	v_mfma_f32_16x16x32_bf16 v[106:109], v[192:195], v[148:151], v[106:109]
	v_mfma_f32_16x16x32_bf16 v[94:97], v[208:211], v[140:143], v[94:97]
	v_mfma_f32_16x16x32_bf16 v[90:93], v[208:211], v[148:151], v[90:93]
	v_mfma_f32_16x16x32_bf16 v[78:81], v[216:219], v[140:143], v[78:81]
	v_mfma_f32_16x16x32_bf16 v[74:77], v[216:219], v[148:151], v[74:77]
	s_setprio 0
	s_setprio 1
	v_mfma_f32_16x16x32_bf16 v[118:121], v[180:183], v[152:155], v[118:121]
	v_mfma_f32_16x16x32_bf16 v[114:117], v[180:183], v[166:169], v[114:117]
	v_mfma_f32_16x16x32_bf16 v[102:105], v[188:191], v[152:155], v[102:105]
	v_mfma_f32_16x16x32_bf16 v[98:101], v[188:191], v[166:169], v[98:101]
	v_mfma_f32_16x16x32_bf16 v[86:89], v[196:199], v[152:155], v[86:89]
	v_mfma_f32_16x16x32_bf16 v[82:85], v[196:199], v[166:169], v[82:85]
	v_mfma_f32_16x16x32_bf16 v[70:73], v[212:215], v[152:155], v[70:73]
	v_mfma_f32_16x16x32_bf16 v[66:69], v[212:215], v[166:169], v[66:69]
	v_mfma_f32_16x16x32_bf16 v[118:121], v[184:187], v[162:165], v[118:121]
	v_mfma_f32_16x16x32_bf16 v[114:117], v[184:187], v[176:179], v[114:117]
	v_mfma_f32_16x16x32_bf16 v[102:105], v[192:195], v[162:165], v[102:105]
	v_mfma_f32_16x16x32_bf16 v[98:101], v[192:195], v[176:179], v[98:101]
	v_mfma_f32_16x16x32_bf16 v[86:89], v[208:211], v[162:165], v[86:89]
	v_mfma_f32_16x16x32_bf16 v[82:85], v[208:211], v[176:179], v[82:85]
	v_mfma_f32_16x16x32_bf16 v[70:73], v[216:219], v[162:165], v[70:73]
	v_mfma_f32_16x16x32_bf16 v[66:69], v[216:219], v[176:179], v[66:69]
	s_setprio 0
	s_barrier
; #define PG8_STAGE(bufoff, gbase, voff) do { _Pragma("unroll") for (int _i = 0; _i < 2; ++_i) \
;         __builtin_amdgcn_global_load_lds((const unsigned*)((const char*)(gbase) + (voff)[_i]), (PG8_LAS unsigned*)(lds + (bufoff) + ldsw + _i * 8192), 16, 0, 0); } while (0)
; #define PG8_LDA(dst, b, h) do { _Pragma("unroll") for (int m = 0; m < 4; ++m) _Pragma("unroll") for (int k = 0; k < 2; ++k) dst[m][k] = *(const PG8_LAS bf16x8*)(lds + PG8_SA(b, h) + aoff + m * 2048 + k * 1024); } while (0)
; #define PG8_LDB(dst, b, h) do { _Pragma("unroll") for (int n = 0; n < 2; ++n) _Pragma("unroll") for (int k = 0; k < 2; ++k) dst[n][k] = *(const PG8_LAS bf16x8*)(lds + PG8_SB(b, h) + boff + n * 2048 + k * 1024); } while (0)
; #define PG8_MMA(ai, bj, At, Bt) do { __builtin_amdgcn_s_setprio(1); _Pragma("unroll") for (int m = 0; m < 4; ++m) _Pragma("unroll") for (int n = 0; n < 2; ++n) _Pragma("unroll") for (int k = 0; k < 2; ++k) \
;         acc[ai][bj][m][n] = __builtin_amdgcn_mfma_f32_16x16x32_bf16(Bt[n][k], At[m][k], acc[ai][bj][m][n], 0, 0, 0); __builtin_amdgcn_s_setprio(0); } while (0)
; #define PG8_WAIT_V(n) asm volatile("s_waitcnt vmcnt(" #n ")" ::: "memory")
; #define PG8_WAIT_L(n) asm volatile("s_waitcnt lgkmcnt(" #n ")" ::: "memory")
; #define PG8_BAR __builtin_amdgcn_s_barrier()
; #define PG8_SCHED __builtin_amdgcn_sched_barrier(0)
; template <class Epi, class Sched, bool ALIGN_EPI = false, bool SP2 = false>
; __device__ __forceinline__ void gemm_phase(PG8_LAS unsigned char* lds, const Gemm g, const Sched& S, const Epi& E, int wave_s) {
;     ...
;             PG8_LDA(At, 0, 1); PG8_STAGE(PG8_SB(0, 0), b2, voffB); PG8_STAGE(PG8_SB(0, 1), b2 + hstepB, voffB); PG8_STAGE(PG8_SA(0, 0), a2, voffA);
;             PG8_WAIT_V(8); PG8_WAIT_L(0); PG8_BAR; PG8_MMA(1, 0, At, B0); PG8_MMA(1, 1, At, B1); PG8_BAR; PG8_SCHED;
;             PG8_LDB(B0, 1, 0); PG8_LDB(B1, 1, 1); PG8_SCHED; PG8_LDA(At, 1, 0); PG8_STAGE(PG8_SA(0, 1), a2 + hstepA, voffA);
;             PG8_WAIT_V(8); PG8_WAIT_L(0); PG8_BAR; PG8_MMA(0, 0, At, B0); PG8_MMA(0, 1, At, B1); PG8_BAR; PG8_SCHED;
	s_add_i32 s16, s34, s37
	v_lshl_add_u64 v[156:157], s[20:21], 0, v[0:1]
	s_mov_b32 m0, s16
	ds_read_b128 v[180:183], v161 offset:16384
	ds_read_b128 v[184:187], v161 offset:17408
	ds_read_b128 v[188:191], v161 offset:18432
	ds_read_b128 v[192:195], v161 offset:19456
	ds_read_b128 v[196:199], v161 offset:20480
	ds_read_b128 v[208:211], v161 offset:21504
	ds_read_b128 v[212:215], v161 offset:22528
	ds_read_b128 v[216:219], v161 offset:23552
	global_load_lds_dwordx4 v[156:157], off
	s_add_i32 m0, s16, 0x2000
	s_add_u32 s16, s20, 0x4000
	v_lshl_add_u64 v[170:171], s[20:21], 0, v[130:131]
	s_addc_u32 s17, s21, 0
	s_add_i32 s34, s35, s37
	global_load_lds_dwordx4 v[170:171], off
	v_lshl_add_u64 v[200:201], s[16:17], 0, v[0:1]
	s_mov_b32 m0, s34
	v_lshl_add_u64 v[220:221], s[24:25], 0, v[228:229]
	global_load_lds_dwordx4 v[200:201], off
	v_lshl_add_u64 v[200:201], s[16:17], 0, v[130:131]
	s_add_i32 m0, s34, 0x2000
	s_nop 0
	global_load_lds_dwordx4 v[200:201], off
	v_lshl_add_u64 v[200:201], s[24:25], 0, v[226:227]
	s_mov_b32 m0, s42
	s_nop 0
	global_load_lds_dwordx4 v[200:201], off
	s_mov_b32 m0, s43
	s_nop 0
	global_load_lds_dwordx4 v[220:221], off
	s_waitcnt vmcnt(8)
	s_waitcnt lgkmcnt(0)
	s_barrier
	s_setprio 1
	s_waitcnt lgkmcnt(0)
	v_mfma_f32_16x16x32_bf16 v[62:65], v[180:183], v[136:139], v[62:65]
	v_mfma_f32_16x16x32_bf16 v[58:61], v[180:183], v[144:147], v[58:61]
	v_mfma_f32_16x16x32_bf16 v[46:49], v[188:191], v[136:139], v[46:49]
	v_mfma_f32_16x16x32_bf16 v[42:45], v[188:191], v[144:147], v[42:45]
	v_mfma_f32_16x16x32_bf16 v[30:33], v[196:199], v[136:139], v[30:33]
	v_mfma_f32_16x16x32_bf16 v[26:29], v[196:199], v[144:147], v[26:29]
	v_mfma_f32_16x16x32_bf16 v[14:17], v[212:215], v[136:139], v[14:17]
	v_mfma_f32_16x16x32_bf16 v[10:13], v[212:215], v[144:147], v[10:13]
	v_mfma_f32_16x16x32_bf16 v[62:65], v[184:187], v[140:143], v[62:65]
	v_mfma_f32_16x16x32_bf16 v[58:61], v[184:187], v[148:151], v[58:61]
	v_mfma_f32_16x16x32_bf16 v[46:49], v[192:195], v[140:143], v[46:49]
	v_mfma_f32_16x16x32_bf16 v[42:45], v[192:195], v[148:151], v[42:45]
	v_mfma_f32_16x16x32_bf16 v[30:33], v[208:211], v[140:143], v[30:33]
	v_mfma_f32_16x16x32_bf16 v[26:29], v[208:211], v[148:151], v[26:29]
	v_mfma_f32_16x16x32_bf16 v[14:17], v[216:219], v[140:143], v[14:17]
	v_mfma_f32_16x16x32_bf16 v[10:13], v[216:219], v[148:151], v[10:13]
	s_setprio 0
	s_setprio 1
	v_mfma_f32_16x16x32_bf16 v[54:57], v[180:183], v[152:155], v[54:57]
	v_mfma_f32_16x16x32_bf16 v[50:53], v[180:183], v[166:169], v[50:53]
	v_mfma_f32_16x16x32_bf16 v[38:41], v[188:191], v[152:155], v[38:41]
	v_mfma_f32_16x16x32_bf16 v[34:37], v[188:191], v[166:169], v[34:37]
	v_mfma_f32_16x16x32_bf16 v[22:25], v[196:199], v[152:155], v[22:25]
	v_mfma_f32_16x16x32_bf16 v[18:21], v[196:199], v[166:169], v[18:21]
	v_mfma_f32_16x16x32_bf16 v[6:9], v[212:215], v[152:155], v[6:9]
	v_mfma_f32_16x16x32_bf16 v[2:5], v[212:215], v[166:169], v[2:5]
	v_mfma_f32_16x16x32_bf16 v[54:57], v[184:187], v[162:165], v[54:57]
	v_mfma_f32_16x16x32_bf16 v[50:53], v[184:187], v[176:179], v[50:53]
	v_mfma_f32_16x16x32_bf16 v[38:41], v[192:195], v[162:165], v[38:41]
	v_mfma_f32_16x16x32_bf16 v[34:37], v[192:195], v[176:179], v[34:37]
	v_mfma_f32_16x16x32_bf16 v[22:25], v[208:211], v[162:165], v[22:25]
	v_mfma_f32_16x16x32_bf16 v[18:21], v[208:211], v[176:179], v[18:21]
	v_mfma_f32_16x16x32_bf16 v[6:9], v[216:219], v[162:165], v[6:9]
	v_mfma_f32_16x16x32_bf16 v[2:5], v[216:219], v[176:179], v[2:5]
	s_setprio 0
	s_barrier
	s_add_i32 s34, 0, 0x18000
	s_add_i32 s35, 0, 0x1c000
	v_add_u32_e32 v148, s34, v159
	v_add_u32_e32 v176, s35, v159
	ds_read_b128 v[136:139], v148
	ds_read_b128 v[140:143], v148 offset:1024
	ds_read_b128 v[144:147], v148 offset:2048
	ds_read_b128 v[148:151], v148 offset:3072
	ds_read_b128 v[152:155], v176
	ds_read_b128 v[162:165], v176 offset:1024
	ds_read_b128 v[166:169], v176 offset:2048
	ds_read_b128 v[176:179], v176 offset:3072
	s_add_u32 s16, s24, 0x4000
	s_addc_u32 s17, s25, 0
	s_mov_b32 m0, s44
	v_lshl_add_u64 v[222:223], s[16:17], 0, v[226:227]
	ds_read_b128 v[180:183], v161 offset:32768
	ds_read_b128 v[184:187], v161 offset:33792
	ds_read_b128 v[188:191], v161 offset:34816
	ds_read_b128 v[192:195], v161 offset:35840
	ds_read_b128 v[196:199], v161 offset:36864
	ds_read_b128 v[208:211], v161 offset:37888
	ds_read_b128 v[212:215], v161 offset:38912
	ds_read_b128 v[216:219], v161 offset:39936
	global_load_lds_dwordx4 v[222:223], off
	v_lshl_add_u64 v[222:223], s[16:17], 0, v[228:229]
	s_mov_b32 m0, s45
	s_nop 0
	global_load_lds_dwordx4 v[222:223], off
	s_waitcnt vmcnt(8)
	s_waitcnt lgkmcnt(0)
	s_barrier
; #define PG8_STAGE(bufoff, gbase, voff) do { _Pragma("unroll") for (int _i = 0; _i < 2; ++_i) \
;         __builtin_amdgcn_global_load_lds((const unsigned*)((const char*)(gbase) + (voff)[_i]), (PG8_LAS unsigned*)(lds + (bufoff) + ldsw + _i * 8192), 16, 0, 0); } while (0)
; #define PG8_LDA(dst, b, h) do { _Pragma("unroll") for (int m = 0; m < 4; ++m) _Pragma("unroll") for (int k = 0; k < 2; ++k) dst[m][k] = *(const PG8_LAS bf16x8*)(lds + PG8_SA(b, h) + aoff + m * 2048 + k * 1024); } while (0)
; #define PG8_MMA(ai, bj, At, Bt) do { __builtin_amdgcn_s_setprio(1); _Pragma("unroll") for (int m = 0; m < 4; ++m) _Pragma("unroll") for (int n = 0; n < 2; ++n) _Pragma("unroll") for (int k = 0; k < 2; ++k) \
;         acc[ai][bj][m][n] = __builtin_amdgcn_mfma_f32_16x16x32_bf16(Bt[n][k], At[m][k], acc[ai][bj][m][n], 0, 0, 0); __builtin_amdgcn_s_setprio(0); } while (0)
; #define PG8_WAIT_V(n) asm volatile("s_waitcnt vmcnt(" #n ")" ::: "memory")
; #define PG8_WAIT_L(n) asm volatile("s_waitcnt lgkmcnt(" #n ")" ::: "memory")
; #define PG8_BAR __builtin_amdgcn_s_barrier()
; #define PG8_SCHED __builtin_amdgcn_sched_barrier(0)
; template <class Epi, class Sched, bool ALIGN_EPI = false, bool SP2 = false>
; __device__ __forceinline__ void gemm_phase(PG8_LAS unsigned char* lds, const Gemm g, const Sched& S, const Epi& E, int wave_s) {
;     ...
;             PG8_WAIT_V(8); PG8_WAIT_L(0); PG8_BAR; PG8_MMA(0, 0, At, B0); PG8_MMA(0, 1, At, B1); PG8_BAR; PG8_SCHED;
;             PG8_LDA(At, 1, 1); PG8_STAGE(PG8_SB(1, 0), b3, voffB); PG8_STAGE(PG8_SB(1, 1), b3 + hstepB, voffB); PG8_STAGE(PG8_SA(1, 0), a3, voffA);
;             PG8_WAIT_V(8); PG8_WAIT_L(0); PG8_BAR; PG8_MMA(1, 0, At, B0); PG8_MMA(1, 1, At, B1); PG8_BAR; PG8_SCHED;
	s_setprio 1
	s_waitcnt lgkmcnt(0)
	v_mfma_f32_16x16x32_bf16 v[126:129], v[180:183], v[136:139], v[126:129]
	v_mfma_f32_16x16x32_bf16 v[122:125], v[180:183], v[144:147], v[122:125]
	v_mfma_f32_16x16x32_bf16 v[110:113], v[188:191], v[136:139], v[110:113]
	v_mfma_f32_16x16x32_bf16 v[106:109], v[188:191], v[144:147], v[106:109]
	v_mfma_f32_16x16x32_bf16 v[94:97], v[196:199], v[136:139], v[94:97]
	v_mfma_f32_16x16x32_bf16 v[90:93], v[196:199], v[144:147], v[90:93]
	v_mfma_f32_16x16x32_bf16 v[78:81], v[212:215], v[136:139], v[78:81]
	v_mfma_f32_16x16x32_bf16 v[74:77], v[212:215], v[144:147], v[74:77]
	v_mfma_f32_16x16x32_bf16 v[126:129], v[184:187], v[140:143], v[126:129]
	v_mfma_f32_16x16x32_bf16 v[122:125], v[184:187], v[148:151], v[122:125]
	v_mfma_f32_16x16x32_bf16 v[110:113], v[192:195], v[140:143], v[110:113]
	v_mfma_f32_16x16x32_bf16 v[106:109], v[192:195], v[148:151], v[106:109]
	v_mfma_f32_16x16x32_bf16 v[94:97], v[208:211], v[140:143], v[94:97]
	v_mfma_f32_16x16x32_bf16 v[90:93], v[208:211], v[148:151], v[90:93]
	v_mfma_f32_16x16x32_bf16 v[78:81], v[216:219], v[140:143], v[78:81]
	v_mfma_f32_16x16x32_bf16 v[74:77], v[216:219], v[148:151], v[74:77]
	s_setprio 0
	s_setprio 1
	v_mfma_f32_16x16x32_bf16 v[118:121], v[180:183], v[152:155], v[118:121]
	v_mfma_f32_16x16x32_bf16 v[114:117], v[180:183], v[166:169], v[114:117]
	v_mfma_f32_16x16x32_bf16 v[102:105], v[188:191], v[152:155], v[102:105]
	v_mfma_f32_16x16x32_bf16 v[98:101], v[188:191], v[166:169], v[98:101]
	v_mfma_f32_16x16x32_bf16 v[86:89], v[196:199], v[152:155], v[86:89]
	v_mfma_f32_16x16x32_bf16 v[82:85], v[196:199], v[166:169], v[82:85]
	v_mfma_f32_16x16x32_bf16 v[70:73], v[212:215], v[152:155], v[70:73]
	v_mfma_f32_16x16x32_bf16 v[66:69], v[212:215], v[166:169], v[66:69]
	v_mfma_f32_16x16x32_bf16 v[118:121], v[184:187], v[162:165], v[118:121]
	v_mfma_f32_16x16x32_bf16 v[114:117], v[184:187], v[176:179], v[114:117]
	v_mfma_f32_16x16x32_bf16 v[102:105], v[192:195], v[162:165], v[102:105]
	v_mfma_f32_16x16x32_bf16 v[98:101], v[192:195], v[176:179], v[98:101]
	v_mfma_f32_16x16x32_bf16 v[86:89], v[208:211], v[162:165], v[86:89]
	v_mfma_f32_16x16x32_bf16 v[82:85], v[208:211], v[176:179], v[82:85]
	v_mfma_f32_16x16x32_bf16 v[70:73], v[216:219], v[162:165], v[70:73]
	v_mfma_f32_16x16x32_bf16 v[66:69], v[216:219], v[176:179], v[66:69]
	s_setprio 0
	s_barrier
	s_add_i32 s16, s34, s37
	s_mov_b64 s[100:101], 0x8000
	v_lshl_add_u64 v[156:157], v[156:157], 0, s[100:101]
	s_mov_b32 m0, s16
	ds_read_b128 v[180:183], v161 offset:49152
	ds_read_b128 v[184:187], v161 offset:50176
	ds_read_b128 v[188:191], v161 offset:51200
	ds_read_b128 v[192:195], v161 offset:52224
	ds_read_b128 v[196:199], v161 offset:53248
	ds_read_b128 v[208:211], v161 offset:54272
	ds_read_b128 v[212:215], v161 offset:55296
	ds_read_b128 v[216:219], v161 offset:56320
	global_load_lds_dwordx4 v[156:157], off
	s_add_i32 m0, s16, 0x2000
	s_add_u32 s16, s20, 0xc000
	v_lshl_add_u64 v[156:157], v[170:171], 0, s[100:101]
	s_addc_u32 s17, s21, 0
	s_add_i32 s20, s35, s37
	global_load_lds_dwordx4 v[156:157], off
	v_lshl_add_u64 v[156:157], s[16:17], 0, v[0:1]
	s_mov_b32 m0, s20
	s_nop 0
	global_load_lds_dwordx4 v[156:157], off
	v_lshl_add_u64 v[156:157], s[16:17], 0, v[130:131]
	s_add_i32 m0, s20, 0x2000
	s_nop 0
	global_load_lds_dwordx4 v[156:157], off
	s_mov_b64 s[100:101], 0x8000
	v_lshl_add_u64 v[156:157], v[200:201], 0, s[100:101]
	s_mov_b32 m0, s48
	s_nop 0
	global_load_lds_dwordx4 v[156:157], off
	v_lshl_add_u64 v[156:157], v[220:221], 0, s[100:101]
	s_mov_b32 m0, s49
	s_nop 0
	global_load_lds_dwordx4 v[156:157], off
	s_waitcnt vmcnt(8)
	s_waitcnt lgkmcnt(0)
	s_barrier
	s_setprio 1
	s_waitcnt lgkmcnt(0)
	v_mfma_f32_16x16x32_bf16 v[62:65], v[180:183], v[136:139], v[62:65]
	v_mfma_f32_16x16x32_bf16 v[58:61], v[180:183], v[144:147], v[58:61]
	v_mfma_f32_16x16x32_bf16 v[46:49], v[188:191], v[136:139], v[46:49]
	v_mfma_f32_16x16x32_bf16 v[42:45], v[188:191], v[144:147], v[42:45]
	v_mfma_f32_16x16x32_bf16 v[30:33], v[196:199], v[136:139], v[30:33]
	v_mfma_f32_16x16x32_bf16 v[26:29], v[196:199], v[144:147], v[26:29]
	v_mfma_f32_16x16x32_bf16 v[14:17], v[212:215], v[136:139], v[14:17]
	v_mfma_f32_16x16x32_bf16 v[10:13], v[212:215], v[144:147], v[10:13]
	v_mfma_f32_16x16x32_bf16 v[62:65], v[184:187], v[140:143], v[62:65]
	v_mfma_f32_16x16x32_bf16 v[58:61], v[184:187], v[148:151], v[58:61]
	v_mfma_f32_16x16x32_bf16 v[46:49], v[192:195], v[140:143], v[46:49]
	v_mfma_f32_16x16x32_bf16 v[42:45], v[192:195], v[148:151], v[42:45]
	v_mfma_f32_16x16x32_bf16 v[30:33], v[208:211], v[140:143], v[30:33]
	v_mfma_f32_16x16x32_bf16 v[26:29], v[208:211], v[148:151], v[26:29]
	v_mfma_f32_16x16x32_bf16 v[14:17], v[216:219], v[140:143], v[14:17]
	v_mfma_f32_16x16x32_bf16 v[10:13], v[216:219], v[148:151], v[10:13]
	s_setprio 0
	s_setprio 1
	v_mfma_f32_16x16x32_bf16 v[54:57], v[180:183], v[152:155], v[54:57]
	v_mfma_f32_16x16x32_bf16 v[50:53], v[180:183], v[166:169], v[50:53]
	v_mfma_f32_16x16x32_bf16 v[38:41], v[188:191], v[152:155], v[38:41]
	v_mfma_f32_16x16x32_bf16 v[34:37], v[188:191], v[166:169], v[34:37]
	v_mfma_f32_16x16x32_bf16 v[22:25], v[196:199], v[152:155], v[22:25]
	v_mfma_f32_16x16x32_bf16 v[18:21], v[196:199], v[166:169], v[18:21]
	v_mfma_f32_16x16x32_bf16 v[6:9], v[212:215], v[152:155], v[6:9]
	v_mfma_f32_16x16x32_bf16 v[2:5], v[212:215], v[166:169], v[2:5]
	v_mfma_f32_16x16x32_bf16 v[54:57], v[184:187], v[162:165], v[54:57]
	v_mfma_f32_16x16x32_bf16 v[50:53], v[184:187], v[176:179], v[50:53]
	v_mfma_f32_16x16x32_bf16 v[38:41], v[192:195], v[162:165], v[38:41]
	v_mfma_f32_16x16x32_bf16 v[34:37], v[192:195], v[176:179], v[34:37]
	v_mfma_f32_16x16x32_bf16 v[22:25], v[208:211], v[162:165], v[22:25]
	v_mfma_f32_16x16x32_bf16 v[18:21], v[208:211], v[176:179], v[18:21]
	v_mfma_f32_16x16x32_bf16 v[6:9], v[216:219], v[162:165], v[6:9]
	v_mfma_f32_16x16x32_bf16 v[2:5], v[216:219], v[176:179], v[2:5]
	s_setprio 0
	s_barrier
	s_add_i32 s41, s41, 2
	s_add_u32 s27, s27, 0x10000
	s_addc_u32 s40, s40, 0
	s_cmpk_gt_u32 s41, 0x55
	s_mov_b64 s[16:17], s[18:19]
	s_cbranch_scc0 .LBB0_358
	s_and_b64 vcc, exec, s[10:11]
	s_cbranch_vccz .LBB0_361
	s_barrier

; #define PG8_STAGE(bufoff, gbase, voff) do { _Pragma("unroll") for (int _i = 0; _i < 2; ++_i) \
;         __builtin_amdgcn_global_load_lds((const unsigned*)((const char*)(gbase) + (voff)[_i]), (PG8_LAS unsigned*)(lds + (bufoff) + ldsw + _i * 8192), 16, 0, 0); } while (0)
; #define PG8_BAR __builtin_amdgcn_s_barrier()
; template <class Epi, class Sched, bool ALIGN_EPI = false, bool SP2 = false>
; __device__ __forceinline__ void gemm_phase(PG8_LAS unsigned char* lds, const Gemm g, const Sched& S, const Epi& E, int wave_s) {
;     ...
;     const int tid = tid_, wid = __builtin_amdgcn_readfirstlane(tid >> 6), lane = tid & 63, wr = wid >> 2, wc = wid & 3, fr = lane & 15, fq = lane >> 4;
;     const int K = g.K, nt = K / BK;
;     unsigned voffA[2], voffB[2];
; #pragma unroll
;     for (int i = 0; i < 2; ++i) { int R, C; stage_rc(tid * 16 + i * 8192, R, C); const int Rb = Epi::PERM ? ((R & ~31) + perm32(R & 31)) : R;
;         voffA[i] = (unsigned)(R * g.lda + C) * 2u; voffB[i] = (unsigned)(Rb * g.ldb + C) * 2u; }
;     const size_t kstep = (size_t)(BK * 2);
;     const size_t hstepA = (size_t)HALF * g.lda * 2, hstepB = (size_t)HALF * g.ldb * 2;
;     const size_t tstepA = 2 * hstepA, tstepB = 2 * hstepB;
;     const unsigned ldsw = (unsigned)wid * 1024u;
;     const int aoff = lds_byte(wr * 64 + fr, fq * 8), boff = lds_byte(wc * 32 + fr, fq * 8);
;     ...
;     Unit cur, nxt; int ui = 0;
;     if (!S.next(0, cur)) return;
;     f32x4 acc[2][2][4][2];
; #pragma unroll
;     for (int a = 0; a < 2; ++a)
; #pragma unroll
;         for (int b = 0; b < 2; ++b)
; #pragma unroll
;             for (int m = 0; m < 4; ++m)
; #pragma unroll
;                 for (int n = 0; n < 2; ++n) acc[a][b][m][n] = (f32x4){0.f, 0.f, 0.f, 0.f};
;     bf16x8 At[4][2], B0[2][2], B1[2][2];
;     const char* cA = (const char*)g.A + (size_t)cur.pm * tstepA; const char* cB = (const char*)g.Bt + (size_t)cur.pn * tstepB;
;     S.a_ready(cur);
;     if constexpr (SP2) {
;         PG8_STAGE(PG8_SB(0, 0), cB, voffB); PG8_STAGE(PG8_SB(0, 1), cB + hstepB, voffB); PG8_STAGE(PG8_SA(0, 0), cA, voffA); PG8_STAGE(PG8_SA(0, 1), cA + hstepA, voffA);
;         if (wr == 1) PG8_BAR;
;         PG8_WAIT_V(2); PG8_BAR;
;         PG8_STAGE(PG8_SB(1, 0), cB + kstep, voffB); PG8_STAGE(PG8_SA(1, 0), cA + kstep, voffA); PG8_STAGE(PG8_SB(1, 1), cB + hstepB + kstep, voffB);
;         PG8_WAIT_V(6); PG8_BAR;
.LBB0_1853:
	s_load_dwordx2 s[8:9], s[82:83], 0xb8
	v_mov_b32_e32 v0, v1
	s_waitcnt lgkmcnt(0)
	v_readlane_b32 s0, v253, 21
	v_mbcnt_lo_u32_b32 v0, -1, v0
	v_mbcnt_hi_u32_b32 v0, -1, v0
	v_or_b32_e32 v0, s0, v0
	s_and_b64 vcc, exec, s[38:39]
	v_readfirstlane_b32 s0, v0
	v_mov_b32_e32 v0, v1
	s_andn2_b32 s0, s0, 63
	v_mbcnt_lo_u32_b32 v0, -1, v0
	v_mbcnt_hi_u32_b32 v0, -1, v0
	v_or_b32_e32 v18, s0, v0
	s_nop 0
	v_readfirstlane_b32 s10, v18
	s_cbranch_vccnz .LBB0_1877
	v_lshlrev_b32_e32 v0, 4, v18
	v_add_u32_e32 v2, 0x2000, v0
	v_ashrrev_i32_e32 v3, 31, v2
	v_lshrrev_b32_e32 v3, 22, v3
	v_add_u32_e32 v3, v2, v3
	v_ashrrev_i32_e32 v10, 10, v3
	v_mul_i32_i24_e32 v3, 0x400, v10
	v_sub_u32_e32 v2, v2, v3
	v_lshrrev_b32_e32 v3, 4, v2
	v_bitop3_b32 v2, v3, v2, 32 bitop3:0x6c
	v_ashrrev_i32_e32 v3, 31, v2
	v_lshrrev_b32_e32 v3, 26, v3
	v_add_u32_e32 v3, v2, v3
	v_ashrrev_i32_e32 v11, 6, v3
	v_lshlrev_b32_e32 v5, 5, v10
	v_and_b32_e32 v3, 0xc0, v3
	v_and_b32_e32 v12, 32, v5
	v_sub_u32_e32 v2, v2, v3
	v_mov_b32_e32 v5, 1
	v_ashrrev_i16_sdwa v2, v5, sext(v2) dst_sel:DWORD dst_unused:UNUSED_PAD src0_sel:DWORD src1_sel:BYTE_0
	v_bfe_i32 v13, v2, 0, 16
	v_bfe_i32 v2, v18, 27, 1
	v_lshrrev_b32_e32 v2, 22, v2
	v_add_u32_e32 v2, v0, v2
	v_and_b32_e32 v2, 0xfffffc00, v2
	v_sub_u32_e32 v0, v0, v2
	s_add_u32 s2, s8, 0x22d90000
	v_lshrrev_b32_e32 v2, 4, v0
	v_ashrrev_i32_e32 v3, 31, v18
	s_addc_u32 s22, s9, 0
	s_mul_i32 s0, s78, 0x2c00000
	v_bitop3_b32 v0, v2, v0, 32 bitop3:0x6c
	v_lshrrev_b32_e32 v3, 26, v3
	s_add_u32 s0, s8, s0
	v_lshlrev_b32_e32 v4, 3, v10
	v_ashrrev_i32_e32 v2, 31, v0
	v_add_u32_e32 v3, v18, v3
	s_addc_u32 s1, s9, 0
	v_and_b32_e32 v4, 0x7ffff0, v4
	v_lshrrev_b32_e32 v2, 26, v2
	v_ashrrev_i32_e32 v15, 6, v3
	s_add_u32 s24, s0, 0xc790000
	v_add_u32_e32 v4, v11, v4
	s_movk_i32 s0, 64
	v_add_u32_e32 v2, v0, v2
	v_lshlrev_b32_e32 v3, 3, v15
	v_lshl_or_b32 v228, v4, 6, v12
	v_add_lshl_u32 v228, v228, v13, 1
	v_mov_b32_e32 v229, 0
	v_mul_lo_u32 v4, v4, s0
	v_ashrrev_i32_e32 v14, 6, v2
	v_and_b32_e32 v3, 0x7ffff0, v3
	s_addc_u32 s25, s1, 0
	s_ashr_i32 s11, s10, 6
	v_or_b32_e32 v4, v4, v12
	v_add_u32_e32 v3, v14, v3
	v_and_b32_e32 v2, 0xc0, v2
	s_ashr_i32 s12, s10, 8
	s_lshl_b32 s40, s11, 10
	s_waitcnt vmcnt(0)
	v_add_lshl_u32 v130, v4, v13, 1
	v_mov_b32_e32 v226, v3
	v_mul_lo_u32 v3, v3, s0
	v_lshlrev_b32_e32 v4, 5, v15
	v_sub_u32_e32 v0, v0, v2
	v_readlane_b32 s0, v255, 22
	v_and_b32_e32 v16, 32, v4
	v_ashrrev_i16_sdwa v0, v5, sext(v0) dst_sel:DWORD dst_unused:UNUSED_PAD src0_sel:DWORD src1_sel:BYTE_0
	s_add_u32 s16, s24, s0
	v_readlane_b32 s0, v255, 20
	v_or_b32_e32 v3, v3, v16
	v_bfe_i32 v17, v0, 0, 16
	s_addc_u32 s17, s25, s0
	s_add_i32 s33, s40, 0
	v_add_lshl_u32 v0, v3, v17, 1
	v_lshl_or_b32 v226, v226, 6, v16
	v_add_lshl_u32 v226, v226, v17, 1
	v_mov_b32_e32 v227, 0
	s_add_i32 m0, s33, 0x10000
	v_mov_b32_e32 v131, v1
	global_load_lds_dwordx4 v0, s[16:17]
	s_add_i32 m0, s33, 0x12000
	s_add_u32 s0, s16, 0x4000
	global_load_lds_dwordx4 v130, s[16:17]
	s_addc_u32 s1, s17, 0
	s_add_i32 m0, s33, 0x14000
	v_lshl_add_u64 v[8:9], s[16:17], 0, v[0:1]
	global_load_lds_dwordx4 v0, s[0:1]
	s_add_i32 m0, s33, 0x16000
	v_lshl_add_u64 v[6:7], s[16:17], 0, v[130:131]
	global_load_lds_dwordx4 v130, s[0:1]
	v_readlane_b32 s0, v255, 19
	s_add_u32 s14, s2, s0
	v_readlane_b32 s0, v255, 16
	s_addc_u32 s15, s22, s0
	s_add_i32 s41, s33, 0x2000
	s_mov_b32 m0, s33
	s_add_u32 s0, s14, 0x4000
	global_load_lds_dwordx4 v226, s[14:15]
	s_mov_b32 m0, s41
	s_addc_u32 s1, s15, 0
	s_add_i32 s42, s33, 0x4000
	global_load_lds_dwordx4 v228, s[14:15]
	s_mov_b32 m0, s42
	s_add_i32 s43, s33, 0x6000
	global_load_lds_dwordx4 v226, s[0:1]
	s_mov_b32 m0, s43
	s_cmp_eq_u32 s12, 1
	global_load_lds_dwordx4 v228, s[0:1]
	v_lshl_add_u64 v[2:3], s[14:15], 0, v[226:227]
	s_cselect_b64 s[0:1], -1, 0
	s_cmp_lg_u32 s12, 1
	v_lshl_add_u64 v[4:5], s[14:15], 0, v[228:229]
	s_cbranch_scc1 .LBB0_1856
	s_barrier
.LBB0_1856:
	s_add_u32 s6, s8, 0x16d90000
	s_addc_u32 s7, s9, 0
	s_mul_i32 s13, s78, 0x48000
	s_add_u32 s8, s8, s13
	s_addc_u32 s9, s9, 0
	v_bfe_u32 v19, v18, 4, 2
	s_add_u32 s44, s8, 0x110000
	v_and_b32_e32 v20, 15, v18
	v_lshlrev_b32_e32 v21, 4, v19
	v_lshlrev_b32_e32 v18, 2, v18
	s_addc_u32 s45, s9, 0
	v_lshl_or_b32 v158, s12, 6, v20
	v_lshl_or_b32 v20, v20, 6, v21
	s_lshl_b32 s8, s12, 13
	v_and_b32_e32 v18, 32, v18
	v_bitop3_b32 v21, v20, s8, v18 bitop3:0xde
	s_lshl_b32 s8, s11, 5
	s_and_b32 s11, s8, 0x60
	s_add_i32 m0, s33, 0x18000
	s_mov_b64 s[100:101], 0x8000
	v_lshl_add_u64 v[8:9], v[8:9], 0, s[100:101]
	s_lshl_b32 s8, s11, 7
	s_waitcnt vmcnt(2)
	s_barrier
	global_load_lds_dwordx4 v[8:9], off
	v_lshl_add_u64 v[6:7], v[6:7], 0, s[100:101]
	s_add_i32 m0, s33, 0x1a000
	s_add_i32 s46, s33, 0x8000
	s_add_i32 s47, s33, 0xa000
	v_bitop3_b32 v159, v20, s8, v18 bitop3:0xde
	global_load_lds_dwordx4 v[6:7], off
	s_mov_b64 s[100:101], 0x8000
	v_lshl_add_u64 v[2:3], v[2:3], 0, s[100:101]
	s_mov_b32 m0, s46
	s_add_u32 s8, s16, 0xc000
	global_load_lds_dwordx4 v[2:3], off
	v_lshl_add_u64 v[2:3], v[4:5], 0, s[100:101]
	s_mov_b32 m0, s47
	s_addc_u32 s9, s17, 0
	global_load_lds_dwordx4 v[2:3], off
	s_add_i32 m0, s33, 0x1c000
	v_lshl_add_u64 v[2:3], s[8:9], 0, v[0:1]
	global_load_lds_dwordx4 v[2:3], off
	v_lshl_add_u64 v[2:3], s[8:9], 0, v[130:131]
	s_add_i32 m0, s33, 0x1e000
	s_movk_i32 s13, 0x1600
	global_load_lds_dwordx4 v[2:3], off
	v_lshrrev_b32_e32 v3, 1, v10
	v_mul_lo_u32 v2, v11, s13
	s_mov_b32 s12, 0x16000
	s_cmpk_lt_u32 s10, 0x100
	v_lshl_or_b32 v160, v19, 2, s11
	v_mad_u64_u32 v[2:3], s[10:11], v3, s12, v[2:3]
	v_or_b32_e32 v2, v2, v12
	v_add_lshl_u32 v2, v2, v13, 1
	v_mov_b32_e32 v3, v1
	s_mov_b64 s[18:19], 0x160080
	s_mov_b64 s[100:101], 0xc000
	v_lshl_add_u64 v[132:133], v[228:229], 0, s[100:101]
	v_lshrrev_b32_e32 v3, 1, v15
	v_mul_lo_u32 v2, v14, s13
	v_mad_u64_u32 v[2:3], s[10:11], v3, s12, v[2:3]
	s_waitcnt vmcnt(6)
	v_or_b32_e32 v2, v2, v16
	v_add_lshl_u32 v2, v2, v17, 1
	v_mov_b32_e32 v3, v1
	v_readlane_b32 s10, v255, 17
	s_cselect_b64 s[8:9], -1, 0
	v_lshl_add_u64 v[134:135], v[226:227], 0, s[100:101]
	s_mov_b32 s48, 0
	v_add_u32_e32 v161, 0, v21
	v_readlane_b32 s26, v255, 21
	s_mov_b32 s51, s10
	s_barrier
	v_readlane_b32 s11, v255, 18
	s_branch .LBB0_1859

; #define PG8_STAGE(bufoff, gbase, voff) do { _Pragma("unroll") for (int _i = 0; _i < 2; ++_i) \
;         __builtin_amdgcn_global_load_lds((const unsigned*)((const char*)(gbase) + (voff)[_i]), (PG8_LAS unsigned*)(lds + (bufoff) + ldsw + _i * 8192), 16, 0, 0); } while (0)
; #define PG8_LDA(dst, b, h) do { _Pragma("unroll") for (int m = 0; m < 4; ++m) _Pragma("unroll") for (int k = 0; k < 2; ++k) dst[m][k] = *(const PG8_LAS bf16x8*)(lds + PG8_SA(b, h) + aoff + m * 2048 + k * 1024); } while (0)
; #define PG8_LDB(dst, b, h) do { _Pragma("unroll") for (int n = 0; n < 2; ++n) _Pragma("unroll") for (int k = 0; k < 2; ++k) dst[n][k] = *(const PG8_LAS bf16x8*)(lds + PG8_SB(b, h) + boff + n * 2048 + k * 1024); } while (0)
; #define PG8_WAIT_V(n) asm volatile("s_waitcnt vmcnt(" #n ")" ::: "memory")
; #define PG8_WAIT_L(n) asm volatile("s_waitcnt lgkmcnt(" #n ")" ::: "memory")
; #define PG8_BAR __builtin_amdgcn_s_barrier()
; #define PG8_SCHED __builtin_amdgcn_sched_barrier(0)
; template <class Epi, class Sched, bool ALIGN_EPI = false, bool SP2 = false>
; __device__ __forceinline__ void gemm_phase(PG8_LAS unsigned char* lds, const Gemm g, const Sched& S, const Epi& E, int wave_s) {
;     ...
;         for (int t = 0; t < nt; t += 2) {
;             const bool last = (t == nt - 2);
;             const char* a1 = cA + (size_t)(t + 1) * kstep;
;             const char* a2 = last ? nA : cA + (size_t)(t + 2) * kstep; const char* b2 = last ? nB : cB + (size_t)(t + 2) * kstep;
;             const char* a3 = a2 + kstep; const char* b3 = b2 + kstep;
;             if (last && has_next) S.a_ready(nxt);
;             if constexpr (Epi::HAS_MID) { if (t == nt / 2) E.mid(acc, cur, wr, wc, fr, fq); }
;             if constexpr (SP2) {
;             PG8_LDB(B0, 0, 0); PG8_LDB(B1, 0, 1); PG8_SCHED; PG8_LDA(At, 0, 0); PG8_STAGE(PG8_SA(1, 1), a1 + hstepA, voffA);
;             PG8_WAIT_V(8); PG8_WAIT_L(0); PG8_BAR; PG8_MMA(0, 0, At, B0); PG8_MMA(0, 1, At, B1); PG8_BAR; PG8_SCHED;
;     ...
;         for (int a = 0; a < 2; ++a)
; #pragma unroll
;             for (int b = 0; b < 2; ++b)
; #pragma unroll
;                 for (int m = 0; m < 4; ++m)
; #pragma unroll
;                     for (int n = 0; n < 2; ++n) acc[a][b][m][n] = (f32x4){0.f, 0.f, 0.f, 0.f};
;         cur = nxt; cA = nA; cB = nB; ++ui;
.LBB0_1869:
	s_add_u32 s27, s16, 0x10000
	v_mov_b32_e32 v2, 0
	s_addc_u32 s38, s17, 0
	s_mov_b32 s39, -2
	v_mov_b32_e32 v3, v2
	v_mov_b32_e32 v4, v2
	v_mov_b32_e32 v5, v2
	v_mov_b32_e32 v6, v2
	v_mov_b32_e32 v7, v2
	v_mov_b32_e32 v8, v2
	v_mov_b32_e32 v9, v2
	v_mov_b32_e32 v18, v2
	v_mov_b32_e32 v19, v2
	v_mov_b32_e32 v20, v2
	v_mov_b32_e32 v21, v2
	v_mov_b32_e32 v22, v2
	v_mov_b32_e32 v23, v2
	v_mov_b32_e32 v24, v2
	v_mov_b32_e32 v25, v2
	v_mov_b32_e32 v34, v2
	v_mov_b32_e32 v35, v2
	v_mov_b32_e32 v36, v2
	v_mov_b32_e32 v37, v2
	v_mov_b32_e32 v38, v2
	v_mov_b32_e32 v39, v2
	v_mov_b32_e32 v40, v2
	v_mov_b32_e32 v41, v2
	v_mov_b32_e32 v50, v2
	v_mov_b32_e32 v51, v2
	v_mov_b32_e32 v52, v2
	v_mov_b32_e32 v53, v2
	v_mov_b32_e32 v54, v2
	v_mov_b32_e32 v55, v2
	v_mov_b32_e32 v56, v2
	v_mov_b32_e32 v57, v2
	v_mov_b32_e32 v10, v2
	v_mov_b32_e32 v11, v2
	v_mov_b32_e32 v12, v2
	v_mov_b32_e32 v13, v2
	v_mov_b32_e32 v14, v2
	v_mov_b32_e32 v15, v2
	v_mov_b32_e32 v16, v2
	v_mov_b32_e32 v17, v2
	v_mov_b32_e32 v26, v2
	v_mov_b32_e32 v27, v2
	v_mov_b32_e32 v28, v2
	v_mov_b32_e32 v29, v2
	v_mov_b32_e32 v30, v2
	v_mov_b32_e32 v31, v2
	v_mov_b32_e32 v32, v2
	v_mov_b32_e32 v33, v2
	v_mov_b32_e32 v42, v2
	v_mov_b32_e32 v43, v2
	v_mov_b32_e32 v44, v2
	v_mov_b32_e32 v45, v2
	v_mov_b32_e32 v46, v2
	v_mov_b32_e32 v47, v2
	v_mov_b32_e32 v48, v2
	v_mov_b32_e32 v49, v2
	v_mov_b32_e32 v58, v2
	v_mov_b32_e32 v59, v2
	v_mov_b32_e32 v60, v2
	v_mov_b32_e32 v61, v2
	v_mov_b32_e32 v62, v2
	v_mov_b32_e32 v63, v2
	v_mov_b32_e32 v64, v2
	v_mov_b32_e32 v65, v2
	v_mov_b32_e32 v66, v2
	v_mov_b32_e32 v67, v2
	v_mov_b32_e32 v68, v2
	v_mov_b32_e32 v69, v2
	v_mov_b32_e32 v70, v2
	v_mov_b32_e32 v71, v2
	v_mov_b32_e32 v72, v2
	v_mov_b32_e32 v73, v2
	v_mov_b32_e32 v82, v2
	v_mov_b32_e32 v83, v2
	v_mov_b32_e32 v84, v2
	v_mov_b32_e32 v85, v2
	v_mov_b32_e32 v86, v2
	v_mov_b32_e32 v87, v2
	v_mov_b32_e32 v88, v2
	v_mov_b32_e32 v89, v2
	v_mov_b32_e32 v98, v2
	v_mov_b32_e32 v99, v2
	v_mov_b32_e32 v100, v2
	v_mov_b32_e32 v101, v2
	v_mov_b32_e32 v102, v2
	v_mov_b32_e32 v103, v2
	v_mov_b32_e32 v104, v2
	v_mov_b32_e32 v105, v2
	v_mov_b32_e32 v114, v2
	v_mov_b32_e32 v115, v2
	v_mov_b32_e32 v116, v2
	v_mov_b32_e32 v117, v2
	v_mov_b32_e32 v118, v2
	v_mov_b32_e32 v119, v2
	v_mov_b32_e32 v120, v2
	v_mov_b32_e32 v121, v2
	v_mov_b32_e32 v74, v2
	v_mov_b32_e32 v75, v2
	v_mov_b32_e32 v76, v2
	v_mov_b32_e32 v77, v2
	v_mov_b32_e32 v78, v2
	v_mov_b32_e32 v79, v2
	v_mov_b32_e32 v80, v2
	v_mov_b32_e32 v81, v2
	v_mov_b32_e32 v90, v2
	v_mov_b32_e32 v91, v2
	v_mov_b32_e32 v92, v2
	v_mov_b32_e32 v93, v2
	v_mov_b32_e32 v94, v2
	v_mov_b32_e32 v95, v2
	v_mov_b32_e32 v96, v2
	v_mov_b32_e32 v97, v2
	v_mov_b32_e32 v106, v2
	v_mov_b32_e32 v107, v2
	v_mov_b32_e32 v108, v2
	v_mov_b32_e32 v109, v2
	v_mov_b32_e32 v110, v2
	v_mov_b32_e32 v111, v2
	v_mov_b32_e32 v112, v2
	v_mov_b32_e32 v113, v2
	v_mov_b32_e32 v122, v2
	v_mov_b32_e32 v123, v2
	v_mov_b32_e32 v124, v2
	v_mov_b32_e32 v125, v2
	v_mov_b32_e32 v126, v2
	v_mov_b32_e32 v127, v2
	v_mov_b32_e32 v128, v2
	v_mov_b32_e32 v129, v2
.LBB0_1870:
	s_add_u32 s16, s14, 0x10000
	s_addc_u32 s17, s15, 0
	s_add_i32 s34, 0, 0x10000
	s_cmpk_eq_i32 s39, 0x54
	s_cselect_b32 s21, s11, s17
	s_cselect_b32 s20, s10, s16
	s_cselect_b32 s19, s13, s38
	s_cselect_b32 s18, s12, s27
	s_add_i32 s35, 0, 0x14000
	v_add_u32_e32 v148, s34, v159
	v_add_u32_e32 v156, s35, v159
	ds_read_b128 v[136:139], v148
	ds_read_b128 v[140:143], v148 offset:1024
	ds_read_b128 v[144:147], v148 offset:2048
	ds_read_b128 v[148:151], v148 offset:3072
	ds_read_b128 v[152:155], v156
	ds_read_b128 v[162:165], v156 offset:1024
	ds_read_b128 v[166:169], v156 offset:2048
	ds_read_b128 v[176:179], v156 offset:3072
	v_lshl_add_u64 v[156:157], s[14:15], 0, v[134:135]
	s_add_i32 m0, s33, 0xc000
	ds_read_b128 v[180:183], v161
	ds_read_b128 v[184:187], v161 offset:1024
	ds_read_b128 v[188:191], v161 offset:2048
	ds_read_b128 v[192:195], v161 offset:3072
	ds_read_b128 v[196:199], v161 offset:4096
	ds_read_b128 v[208:211], v161 offset:5120
	ds_read_b128 v[212:215], v161 offset:6144
	ds_read_b128 v[216:219], v161 offset:7168
	global_load_lds_dwordx4 v[156:157], off
	v_lshl_add_u64 v[156:157], s[14:15], 0, v[132:133]
	s_add_i32 m0, s33, 0xe000
	s_nop 0
	global_load_lds_dwordx4 v[156:157], off
	s_waitcnt vmcnt(8)
	s_waitcnt lgkmcnt(0)
	s_barrier
	s_setprio 1
	s_waitcnt lgkmcnt(0)
	v_mfma_f32_16x16x32_bf16 v[126:129], v[180:183], v[136:139], v[126:129]
	v_mfma_f32_16x16x32_bf16 v[122:125], v[180:183], v[144:147], v[122:125]
	v_mfma_f32_16x16x32_bf16 v[110:113], v[188:191], v[136:139], v[110:113]
	v_mfma_f32_16x16x32_bf16 v[106:109], v[188:191], v[144:147], v[106:109]
	v_mfma_f32_16x16x32_bf16 v[94:97], v[196:199], v[136:139], v[94:97]
	v_mfma_f32_16x16x32_bf16 v[90:93], v[196:199], v[144:147], v[90:93]
	v_mfma_f32_16x16x32_bf16 v[78:81], v[212:215], v[136:139], v[78:81]
	v_mfma_f32_16x16x32_bf16 v[74:77], v[212:215], v[144:147], v[74:77]
	v_mfma_f32_16x16x32_bf16 v[126:129], v[184:187], v[140:143], v[126:129]
	v_mfma_f32_16x16x32_bf16 v[122:125], v[184:187], v[148:151], v[122:125]
	v_mfma_f32_16x16x32_bf16 v[110:113], v[192:195], v[140:143], v[110:113]
	v_mfma_f32_16x16x32_bf16 v[106:109], v[192:195], v[148:151], v[106:109]
	v_mfma_f32_16x16x32_bf16 v[94:97], v[208:211], v[140:143], v[94:97]
	v_mfma_f32_16x16x32_bf16 v[90:93], v[208:211], v[148:151], v[90:93]
	v_mfma_f32_16x16x32_bf16 v[78:81], v[216:219], v[140:143], v[78:81]
	v_mfma_f32_16x16x32_bf16 v[74:77], v[216:219], v[148:151], v[74:77]
	s_setprio 0
	s_setprio 1
	v_mfma_f32_16x16x32_bf16 v[118:121], v[180:183], v[152:155], v[118:121]
	v_mfma_f32_16x16x32_bf16 v[114:117], v[180:183], v[166:169], v[114:117]
	v_mfma_f32_16x16x32_bf16 v[102:105], v[188:191], v[152:155], v[102:105]
	v_mfma_f32_16x16x32_bf16 v[98:101], v[188:191], v[166:169], v[98:101]
	v_mfma_f32_16x16x32_bf16 v[86:89], v[196:199], v[152:155], v[86:89]
	v_mfma_f32_16x16x32_bf16 v[82:85], v[196:199], v[166:169], v[82:85]
	v_mfma_f32_16x16x32_bf16 v[70:73], v[212:215], v[152:155], v[70:73]
	v_mfma_f32_16x16x32_bf16 v[66:69], v[212:215], v[166:169], v[66:69]
	v_mfma_f32_16x16x32_bf16 v[118:121], v[184:187], v[162:165], v[118:121]
	v_mfma_f32_16x16x32_bf16 v[114:117], v[184:187], v[176:179], v[114:117]
	v_mfma_f32_16x16x32_bf16 v[102:105], v[192:195], v[162:165], v[102:105]
	v_mfma_f32_16x16x32_bf16 v[98:101], v[192:195], v[176:179], v[98:101]
	v_mfma_f32_16x16x32_bf16 v[86:89], v[208:211], v[162:165], v[86:89]
	v_mfma_f32_16x16x32_bf16 v[82:85], v[208:211], v[176:179], v[82:85]
	v_mfma_f32_16x16x32_bf16 v[70:73], v[216:219], v[162:165], v[70:73]
	v_mfma_f32_16x16x32_bf16 v[66:69], v[216:219], v[176:179], v[66:69]
	s_setprio 0
	s_barrier
; #define PG8_STAGE(bufoff, gbase, voff) do { _Pragma("unroll") for (int _i = 0; _i < 2; ++_i) \
;         __builtin_amdgcn_global_load_lds((const unsigned*)((const char*)(gbase) + (voff)[_i]), (PG8_LAS unsigned*)(lds + (bufoff) + ldsw + _i * 8192), 16, 0, 0); } while (0)
; #define PG8_LDA(dst, b, h) do { _Pragma("unroll") for (int m = 0; m < 4; ++m) _Pragma("unroll") for (int k = 0; k < 2; ++k) dst[m][k] = *(const PG8_LAS bf16x8*)(lds + PG8_SA(b, h) + aoff + m * 2048 + k * 1024); } while (0)
; #define PG8_LDB(dst, b, h) do { _Pragma("unroll") for (int n = 0; n < 2; ++n) _Pragma("unroll") for (int k = 0; k < 2; ++k) dst[n][k] = *(const PG8_LAS bf16x8*)(lds + PG8_SB(b, h) + boff + n * 2048 + k * 1024); } while (0)
; #define PG8_MMA(ai, bj, At, Bt) do { __builtin_amdgcn_s_setprio(1); _Pragma("unroll") for (int m = 0; m < 4; ++m) _Pragma("unroll") for (int n = 0; n < 2; ++n) _Pragma("unroll") for (int k = 0; k < 2; ++k) \
;         acc[ai][bj][m][n] = __builtin_amdgcn_mfma_f32_16x16x32_bf16(Bt[n][k], At[m][k], acc[ai][bj][m][n], 0, 0, 0); __builtin_amdgcn_s_setprio(0); } while (0)
; #define PG8_WAIT_V(n) asm volatile("s_waitcnt vmcnt(" #n ")" ::: "memory")
; #define PG8_WAIT_L(n) asm volatile("s_waitcnt lgkmcnt(" #n ")" ::: "memory")
; #define PG8_BAR __builtin_amdgcn_s_barrier()
; #define PG8_SCHED __builtin_amdgcn_sched_barrier(0)
; template <class Epi, class Sched, bool ALIGN_EPI = false, bool SP2 = false>
; __device__ __forceinline__ void gemm_phase(PG8_LAS unsigned char* lds, const Gemm g, const Sched& S, const Epi& E, int wave_s) {
;     ...
;             PG8_LDA(At, 0, 1); PG8_STAGE(PG8_SB(0, 0), b2, voffB); PG8_STAGE(PG8_SB(0, 1), b2 + hstepB, voffB); PG8_STAGE(PG8_SA(0, 0), a2, voffA);
;             PG8_WAIT_V(8); PG8_WAIT_L(0); PG8_BAR; PG8_MMA(1, 0, At, B0); PG8_MMA(1, 1, At, B1); PG8_BAR; PG8_SCHED;
;             PG8_LDB(B0, 1, 0); PG8_LDB(B1, 1, 1); PG8_SCHED; PG8_LDA(At, 1, 0); PG8_STAGE(PG8_SA(0, 1), a2 + hstepA, voffA);
;             PG8_WAIT_V(8); PG8_WAIT_L(0); PG8_BAR; PG8_MMA(0, 0, At, B0); PG8_MMA(0, 1, At, B1); PG8_BAR; PG8_SCHED;
	s_add_i32 s14, s34, s40
	v_lshl_add_u64 v[156:157], s[18:19], 0, v[0:1]
	s_mov_b32 m0, s14
	ds_read_b128 v[180:183], v161 offset:16384
	ds_read_b128 v[184:187], v161 offset:17408
	ds_read_b128 v[188:191], v161 offset:18432
	ds_read_b128 v[192:195], v161 offset:19456
	ds_read_b128 v[196:199], v161 offset:20480
	ds_read_b128 v[208:211], v161 offset:21504
	ds_read_b128 v[212:215], v161 offset:22528
	ds_read_b128 v[216:219], v161 offset:23552
	global_load_lds_dwordx4 v[156:157], off
	s_add_i32 m0, s14, 0x2000
	s_add_u32 s14, s18, 0x4000
	v_lshl_add_u64 v[170:171], s[18:19], 0, v[130:131]
	s_addc_u32 s15, s19, 0
	s_add_i32 s34, s35, s40
	global_load_lds_dwordx4 v[170:171], off
	v_lshl_add_u64 v[200:201], s[14:15], 0, v[0:1]
	s_mov_b32 m0, s34
	v_lshl_add_u64 v[220:221], s[20:21], 0, v[228:229]
	global_load_lds_dwordx4 v[200:201], off
	v_lshl_add_u64 v[200:201], s[14:15], 0, v[130:131]
	s_add_i32 m0, s34, 0x2000
	s_nop 0
	global_load_lds_dwordx4 v[200:201], off
	v_lshl_add_u64 v[200:201], s[20:21], 0, v[226:227]
	s_mov_b32 m0, s33
	s_nop 0
	global_load_lds_dwordx4 v[200:201], off
	s_mov_b32 m0, s41
	s_nop 0
	global_load_lds_dwordx4 v[220:221], off
	s_waitcnt vmcnt(8)
	s_waitcnt lgkmcnt(0)
	s_barrier
	s_setprio 1
	s_waitcnt lgkmcnt(0)
	v_mfma_f32_16x16x32_bf16 v[62:65], v[180:183], v[136:139], v[62:65]
	v_mfma_f32_16x16x32_bf16 v[58:61], v[180:183], v[144:147], v[58:61]
	v_mfma_f32_16x16x32_bf16 v[46:49], v[188:191], v[136:139], v[46:49]
	v_mfma_f32_16x16x32_bf16 v[42:45], v[188:191], v[144:147], v[42:45]
	v_mfma_f32_16x16x32_bf16 v[30:33], v[196:199], v[136:139], v[30:33]
	v_mfma_f32_16x16x32_bf16 v[26:29], v[196:199], v[144:147], v[26:29]
	v_mfma_f32_16x16x32_bf16 v[14:17], v[212:215], v[136:139], v[14:17]
	v_mfma_f32_16x16x32_bf16 v[10:13], v[212:215], v[144:147], v[10:13]
	v_mfma_f32_16x16x32_bf16 v[62:65], v[184:187], v[140:143], v[62:65]
	v_mfma_f32_16x16x32_bf16 v[58:61], v[184:187], v[148:151], v[58:61]
	v_mfma_f32_16x16x32_bf16 v[46:49], v[192:195], v[140:143], v[46:49]
	v_mfma_f32_16x16x32_bf16 v[42:45], v[192:195], v[148:151], v[42:45]
	v_mfma_f32_16x16x32_bf16 v[30:33], v[208:211], v[140:143], v[30:33]
	v_mfma_f32_16x16x32_bf16 v[26:29], v[208:211], v[148:151], v[26:29]
	v_mfma_f32_16x16x32_bf16 v[14:17], v[216:219], v[140:143], v[14:17]
	v_mfma_f32_16x16x32_bf16 v[10:13], v[216:219], v[148:151], v[10:13]
	s_setprio 0
	s_setprio 1
	v_mfma_f32_16x16x32_bf16 v[54:57], v[180:183], v[152:155], v[54:57]
	v_mfma_f32_16x16x32_bf16 v[50:53], v[180:183], v[166:169], v[50:53]
	v_mfma_f32_16x16x32_bf16 v[38:41], v[188:191], v[152:155], v[38:41]
	v_mfma_f32_16x16x32_bf16 v[34:37], v[188:191], v[166:169], v[34:37]
	v_mfma_f32_16x16x32_bf16 v[22:25], v[196:199], v[152:155], v[22:25]
	v_mfma_f32_16x16x32_bf16 v[18:21], v[196:199], v[166:169], v[18:21]
	v_mfma_f32_16x16x32_bf16 v[6:9], v[212:215], v[152:155], v[6:9]
	v_mfma_f32_16x16x32_bf16 v[2:5], v[212:215], v[166:169], v[2:5]
	v_mfma_f32_16x16x32_bf16 v[54:57], v[184:187], v[162:165], v[54:57]
	v_mfma_f32_16x16x32_bf16 v[50:53], v[184:187], v[176:179], v[50:53]
	v_mfma_f32_16x16x32_bf16 v[38:41], v[192:195], v[162:165], v[38:41]
	v_mfma_f32_16x16x32_bf16 v[34:37], v[192:195], v[176:179], v[34:37]
	v_mfma_f32_16x16x32_bf16 v[22:25], v[208:211], v[162:165], v[22:25]
	v_mfma_f32_16x16x32_bf16 v[18:21], v[208:211], v[176:179], v[18:21]
	v_mfma_f32_16x16x32_bf16 v[6:9], v[216:219], v[162:165], v[6:9]
	v_mfma_f32_16x16x32_bf16 v[2:5], v[216:219], v[176:179], v[2:5]
	s_setprio 0
	s_barrier
	s_add_i32 s34, 0, 0x18000
	s_add_i32 s35, 0, 0x1c000
	v_add_u32_e32 v148, s34, v159
	v_add_u32_e32 v176, s35, v159
	ds_read_b128 v[136:139], v148
	ds_read_b128 v[140:143], v148 offset:1024
	ds_read_b128 v[144:147], v148 offset:2048
	ds_read_b128 v[148:151], v148 offset:3072
	ds_read_b128 v[152:155], v176
	ds_read_b128 v[162:165], v176 offset:1024
	ds_read_b128 v[166:169], v176 offset:2048
	ds_read_b128 v[176:179], v176 offset:3072
	s_add_u32 s14, s20, 0x4000
	s_addc_u32 s15, s21, 0
	s_mov_b32 m0, s42
	v_lshl_add_u64 v[222:223], s[14:15], 0, v[226:227]
	ds_read_b128 v[180:183], v161 offset:32768
	ds_read_b128 v[184:187], v161 offset:33792
	ds_read_b128 v[188:191], v161 offset:34816
	ds_read_b128 v[192:195], v161 offset:35840
	ds_read_b128 v[196:199], v161 offset:36864
	ds_read_b128 v[208:211], v161 offset:37888
	ds_read_b128 v[212:215], v161 offset:38912
	ds_read_b128 v[216:219], v161 offset:39936
	global_load_lds_dwordx4 v[222:223], off
	v_lshl_add_u64 v[222:223], s[14:15], 0, v[228:229]
	s_mov_b32 m0, s43
	s_nop 0
	global_load_lds_dwordx4 v[222:223], off
	s_waitcnt vmcnt(8)
	s_waitcnt lgkmcnt(0)
	s_barrier
; #define PG8_STAGE(bufoff, gbase, voff) do { _Pragma("unroll") for (int _i = 0; _i < 2; ++_i) \
;         __builtin_amdgcn_global_load_lds((const unsigned*)((const char*)(gbase) + (voff)[_i]), (PG8_LAS unsigned*)(lds + (bufoff) + ldsw + _i * 8192), 16, 0, 0); } while (0)
; #define PG8_LDA(dst, b, h) do { _Pragma("unroll") for (int m = 0; m < 4; ++m) _Pragma("unroll") for (int k = 0; k < 2; ++k) dst[m][k] = *(const PG8_LAS bf16x8*)(lds + PG8_SA(b, h) + aoff + m * 2048 + k * 1024); } while (0)
; #define PG8_MMA(ai, bj, At, Bt) do { __builtin_amdgcn_s_setprio(1); _Pragma("unroll") for (int m = 0; m < 4; ++m) _Pragma("unroll") for (int n = 0; n < 2; ++n) _Pragma("unroll") for (int k = 0; k < 2; ++k) \
;         acc[ai][bj][m][n] = __builtin_amdgcn_mfma_f32_16x16x32_bf16(Bt[n][k], At[m][k], acc[ai][bj][m][n], 0, 0, 0); __builtin_amdgcn_s_setprio(0); } while (0)
; #define PG8_WAIT_V(n) asm volatile("s_waitcnt vmcnt(" #n ")" ::: "memory")
; #define PG8_WAIT_L(n) asm volatile("s_waitcnt lgkmcnt(" #n ")" ::: "memory")
; #define PG8_BAR __builtin_amdgcn_s_barrier()
; #define PG8_SCHED __builtin_amdgcn_sched_barrier(0)
; template <class Epi, class Sched, bool ALIGN_EPI = false, bool SP2 = false>
; __device__ __forceinline__ void gemm_phase(PG8_LAS unsigned char* lds, const Gemm g, const Sched& S, const Epi& E, int wave_s) {
;     ...
;             PG8_WAIT_V(8); PG8_WAIT_L(0); PG8_BAR; PG8_MMA(0, 0, At, B0); PG8_MMA(0, 1, At, B1); PG8_BAR; PG8_SCHED;
;             PG8_LDA(At, 1, 1); PG8_STAGE(PG8_SB(1, 0), b3, voffB); PG8_STAGE(PG8_SB(1, 1), b3 + hstepB, voffB); PG8_STAGE(PG8_SA(1, 0), a3, voffA);
;             PG8_WAIT_V(8); PG8_WAIT_L(0); PG8_BAR; PG8_MMA(1, 0, At, B0); PG8_MMA(1, 1, At, B1); PG8_BAR; PG8_SCHED;
	s_setprio 1
	s_waitcnt lgkmcnt(0)
	v_mfma_f32_16x16x32_bf16 v[126:129], v[180:183], v[136:139], v[126:129]
	v_mfma_f32_16x16x32_bf16 v[122:125], v[180:183], v[144:147], v[122:125]
	v_mfma_f32_16x16x32_bf16 v[110:113], v[188:191], v[136:139], v[110:113]
	v_mfma_f32_16x16x32_bf16 v[106:109], v[188:191], v[144:147], v[106:109]
	v_mfma_f32_16x16x32_bf16 v[94:97], v[196:199], v[136:139], v[94:97]
	v_mfma_f32_16x16x32_bf16 v[90:93], v[196:199], v[144:147], v[90:93]
	v_mfma_f32_16x16x32_bf16 v[78:81], v[212:215], v[136:139], v[78:81]
	v_mfma_f32_16x16x32_bf16 v[74:77], v[212:215], v[144:147], v[74:77]
	v_mfma_f32_16x16x32_bf16 v[126:129], v[184:187], v[140:143], v[126:129]
	v_mfma_f32_16x16x32_bf16 v[122:125], v[184:187], v[148:151], v[122:125]
	v_mfma_f32_16x16x32_bf16 v[110:113], v[192:195], v[140:143], v[110:113]
	v_mfma_f32_16x16x32_bf16 v[106:109], v[192:195], v[148:151], v[106:109]
	v_mfma_f32_16x16x32_bf16 v[94:97], v[208:211], v[140:143], v[94:97]
	v_mfma_f32_16x16x32_bf16 v[90:93], v[208:211], v[148:151], v[90:93]
	v_mfma_f32_16x16x32_bf16 v[78:81], v[216:219], v[140:143], v[78:81]
	v_mfma_f32_16x16x32_bf16 v[74:77], v[216:219], v[148:151], v[74:77]
	s_setprio 0
	s_setprio 1
	v_mfma_f32_16x16x32_bf16 v[118:121], v[180:183], v[152:155], v[118:121]
	v_mfma_f32_16x16x32_bf16 v[114:117], v[180:183], v[166:169], v[114:117]
	v_mfma_f32_16x16x32_bf16 v[102:105], v[188:191], v[152:155], v[102:105]
	v_mfma_f32_16x16x32_bf16 v[98:101], v[188:191], v[166:169], v[98:101]
	v_mfma_f32_16x16x32_bf16 v[86:89], v[196:199], v[152:155], v[86:89]
	v_mfma_f32_16x16x32_bf16 v[82:85], v[196:199], v[166:169], v[82:85]
	v_mfma_f32_16x16x32_bf16 v[70:73], v[212:215], v[152:155], v[70:73]
	v_mfma_f32_16x16x32_bf16 v[66:69], v[212:215], v[166:169], v[66:69]
	v_mfma_f32_16x16x32_bf16 v[118:121], v[184:187], v[162:165], v[118:121]
	v_mfma_f32_16x16x32_bf16 v[114:117], v[184:187], v[176:179], v[114:117]
	v_mfma_f32_16x16x32_bf16 v[102:105], v[192:195], v[162:165], v[102:105]
	v_mfma_f32_16x16x32_bf16 v[98:101], v[192:195], v[176:179], v[98:101]
	v_mfma_f32_16x16x32_bf16 v[86:89], v[208:211], v[162:165], v[86:89]
	v_mfma_f32_16x16x32_bf16 v[82:85], v[208:211], v[176:179], v[82:85]
	v_mfma_f32_16x16x32_bf16 v[70:73], v[216:219], v[162:165], v[70:73]
	v_mfma_f32_16x16x32_bf16 v[66:69], v[216:219], v[176:179], v[66:69]
	s_setprio 0
	s_barrier
	s_add_i32 s14, s34, s40
	s_mov_b64 s[100:101], 0x8000
	v_lshl_add_u64 v[156:157], v[156:157], 0, s[100:101]
	s_mov_b32 m0, s14
	ds_read_b128 v[180:183], v161 offset:49152
	ds_read_b128 v[184:187], v161 offset:50176
	ds_read_b128 v[188:191], v161 offset:51200
	ds_read_b128 v[192:195], v161 offset:52224
	ds_read_b128 v[196:199], v161 offset:53248
	ds_read_b128 v[208:211], v161 offset:54272
	ds_read_b128 v[212:215], v161 offset:55296
	ds_read_b128 v[216:219], v161 offset:56320
	global_load_lds_dwordx4 v[156:157], off
	s_add_i32 m0, s14, 0x2000
	s_add_u32 s14, s18, 0xc000
	v_lshl_add_u64 v[156:157], v[170:171], 0, s[100:101]
	s_addc_u32 s15, s19, 0
	s_add_i32 s18, s35, s40
	global_load_lds_dwordx4 v[156:157], off
	v_lshl_add_u64 v[156:157], s[14:15], 0, v[0:1]
	s_mov_b32 m0, s18
	s_nop 0
	global_load_lds_dwordx4 v[156:157], off
	v_lshl_add_u64 v[156:157], s[14:15], 0, v[130:131]
	s_add_i32 m0, s18, 0x2000
	s_nop 0
	global_load_lds_dwordx4 v[156:157], off
	s_mov_b64 s[100:101], 0x8000
	v_lshl_add_u64 v[156:157], v[200:201], 0, s[100:101]
	s_mov_b32 m0, s46
	s_nop 0
	global_load_lds_dwordx4 v[156:157], off
	v_lshl_add_u64 v[156:157], v[220:221], 0, s[100:101]
	s_mov_b32 m0, s47
	s_nop 0
	global_load_lds_dwordx4 v[156:157], off
	s_waitcnt vmcnt(8)
	s_waitcnt lgkmcnt(0)
	s_barrier
	s_setprio 1
	s_waitcnt lgkmcnt(0)
	v_mfma_f32_16x16x32_bf16 v[62:65], v[180:183], v[136:139], v[62:65]
	v_mfma_f32_16x16x32_bf16 v[58:61], v[180:183], v[144:147], v[58:61]
	v_mfma_f32_16x16x32_bf16 v[46:49], v[188:191], v[136:139], v[46:49]
	v_mfma_f32_16x16x32_bf16 v[42:45], v[188:191], v[144:147], v[42:45]
	v_mfma_f32_16x16x32_bf16 v[30:33], v[196:199], v[136:139], v[30:33]
	v_mfma_f32_16x16x32_bf16 v[26:29], v[196:199], v[144:147], v[26:29]
	v_mfma_f32_16x16x32_bf16 v[14:17], v[212:215], v[136:139], v[14:17]
	v_mfma_f32_16x16x32_bf16 v[10:13], v[212:215], v[144:147], v[10:13]
	v_mfma_f32_16x16x32_bf16 v[62:65], v[184:187], v[140:143], v[62:65]
	v_mfma_f32_16x16x32_bf16 v[58:61], v[184:187], v[148:151], v[58:61]
	v_mfma_f32_16x16x32_bf16 v[46:49], v[192:195], v[140:143], v[46:49]
	v_mfma_f32_16x16x32_bf16 v[42:45], v[192:195], v[148:151], v[42:45]
	v_mfma_f32_16x16x32_bf16 v[30:33], v[208:211], v[140:143], v[30:33]
	v_mfma_f32_16x16x32_bf16 v[26:29], v[208:211], v[148:151], v[26:29]
	v_mfma_f32_16x16x32_bf16 v[14:17], v[216:219], v[140:143], v[14:17]
	v_mfma_f32_16x16x32_bf16 v[10:13], v[216:219], v[148:151], v[10:13]
	s_setprio 0
	s_setprio 1
	v_mfma_f32_16x16x32_bf16 v[54:57], v[180:183], v[152:155], v[54:57]
	v_mfma_f32_16x16x32_bf16 v[50:53], v[180:183], v[166:169], v[50:53]
	v_mfma_f32_16x16x32_bf16 v[38:41], v[188:191], v[152:155], v[38:41]
	v_mfma_f32_16x16x32_bf16 v[34:37], v[188:191], v[166:169], v[34:37]
	v_mfma_f32_16x16x32_bf16 v[22:25], v[196:199], v[152:155], v[22:25]
	v_mfma_f32_16x16x32_bf16 v[18:21], v[196:199], v[166:169], v[18:21]
	v_mfma_f32_16x16x32_bf16 v[6:9], v[212:215], v[152:155], v[6:9]
	v_mfma_f32_16x16x32_bf16 v[2:5], v[212:215], v[166:169], v[2:5]
	v_mfma_f32_16x16x32_bf16 v[54:57], v[184:187], v[162:165], v[54:57]
	v_mfma_f32_16x16x32_bf16 v[50:53], v[184:187], v[176:179], v[50:53]
	v_mfma_f32_16x16x32_bf16 v[38:41], v[192:195], v[162:165], v[38:41]
	v_mfma_f32_16x16x32_bf16 v[34:37], v[192:195], v[176:179], v[34:37]
	v_mfma_f32_16x16x32_bf16 v[22:25], v[208:211], v[162:165], v[22:25]
	v_mfma_f32_16x16x32_bf16 v[18:21], v[208:211], v[176:179], v[18:21]
	v_mfma_f32_16x16x32_bf16 v[6:9], v[216:219], v[162:165], v[6:9]
	v_mfma_f32_16x16x32_bf16 v[2:5], v[216:219], v[176:179], v[2:5]
	s_setprio 0
	s_barrier
	s_add_i32 s39, s39, 2
	s_add_u32 s27, s27, 0x10000
	s_addc_u32 s38, s38, 0
	s_cmpk_gt_u32 s39, 0x55
	s_mov_b64 s[14:15], s[16:17]
	s_cbranch_scc0 .LBB0_1870
	s_and_b64 vcc, exec, s[8:9]
	s_cbranch_vccz .LBB0_1873
	s_barrier
